# layer-1 w_br/w_out conversion moved into the in GEMM tail of layer 1 so the up GEMM last round shares its units 2-way in both layers; attention xor-16/32 reductions through v_permlane swaps
# speedup vs baseline: 1.0077x; 1.0030x over previous
; #define LAS __attribute__((address_space(3)))
; __device__ __forceinline__ int opaque_tid(int wv) { asm volatile("" : "+s"(wv)); unsigned z = 0u; asm volatile("" : "+v"(z)); const int l = __builtin_amdgcn_mbcnt_hi(~0u, __builtin_amdgcn_mbcnt_lo(~0u, z)); return (wv << 6) | l; }
; __device__ __forceinline__ void convert_weight(int wv, const float* __restrict__ src, int ldsrc, int Ksrc, bf16_t* dst, int ldd, int koff, int ntn, const float* kscale, int mode, LAS float* tile, int pidx, int pcnt) {
;     const int tid = opaque_tid(wv); const int ntk = Ksrc / 128; const int total = ntn * ntk; const int G = pcnt;
;     const int kk0 = tid >> 4, n4 = (tid & 15) * 4;
;     f32x4 v[4]; float ks[4];
;     auto prefetch = [&](int t) {
;         const int tn = t % ntn, tk = t / ntn; const int n0 = tn * 64, k0 = tk * 128;
;         int scol = n0, nvalid = 64;
;         if (mode == 1) { if (n0 < 5632) scol = n0; else if (n0 < 13312) scol = n0 + 8; else if (n0 == 13312) { scol = 5632; nvalid = 8; } else { scol = 0; nvalid = 0; } }
; #pragma unroll
;         for (int i = 0; i < 4; ++i) { const int kk = kk0 + i * 32; v[i] = (f32x4){0.f, 0.f, 0.f, 0.f};
;             if (n4 < nvalid) v[i] = *(const f32x4*)(src + (size_t)(k0 + kk) * ldsrc + scol + n4);
;             ks[i] = kscale ? kscale[k0 + kk] : 1.0f; }
;     };
;     int t = pidx; int buf = 0;
;     if (t < total) prefetch(t);
; __device__ __forceinline__ void convert_layer(int wv, PP P, int L, int mask, LAS float* tile, int pidx, int pcnt) {
;     ...
;         convert_weight(wv, P->w_br_a + (size_t)L * 512 * D, D, 512, wbr, D, 0, D / 64, nullptr, 0, tile, pidx, pcnt);
.LBB0_192:
	v_cndmask_b32_e64 v0, 0, 1, s[10:11]
	v_cmp_ne_u32_e64 s[4:5], 1, v0
	s_andn2_b64 vcc, exec, s[10:11]
	s_nop 0
	v_writelane_b32 v254, s4, 30
	s_nop 1
	v_writelane_b32 v254, s5, 31
	s_mov_b32 s6, s81
	v_readlane_b32 s4, v254, 3
	s_cmp_lt_i32 s6, s4
	v_readlane_b32 s8, v254, 1
	s_cselect_b64 s[4:5], -1, 0
	v_readlane_b32 s9, v254, 2
	s_or_b64 s[4:5], s[8:9], s[4:5]
	s_and_b64 vcc, exec, s[4:5]
	s_cbranch_vccnz .LBB0_223
	s_mov_b64 s[4:5], s[0:1]
	v_readlane_b32 s7, v254, 3
	s_sub_i32 s20, s6, s7
	s_load_dwordx2 s[6:7], s[4:5], 0x98
	s_cmpk_lt_i32 s20, 0x80
	s_mov_b32 s16, s95
	v_mov_b32_e32 v0, v3
	s_cselect_b64 s[8:9], -1, 0
	s_cmpk_gt_i32 s20, 0x7f
	s_cbranch_scc1 .LBB0_201
	v_mbcnt_lo_u32_b32 v0, -1, v0
	v_mbcnt_hi_u32_b32 v20, -1, v0
	s_waitcnt lgkmcnt(0)
	s_add_u32 s12, s6, 0x4200000
	v_lshl_or_b32 v21, s16, 6, v20
	s_sext_i32_i16 s16, s20
	s_addc_u32 s13, s7, 0
	s_bfe_u32 s16, s16, 0x5001a
	s_add_i32 s16, s20, s16
	s_sext_i32_i16 s17, s16
	s_load_dwordx2 s[14:15], s[4:5], 0x48
	s_waitcnt lgkmcnt(0)
	s_mul_i32 s98, s2, 0x400000
	s_add_u32 s14, s14, s98
	s_addc_u32 s15, s15, 0
	v_ashrrev_i32_e32 v22, 4, v21
	s_and_b32 s16, s16, 0xffe0
	s_lshl_b32 s17, s17, 2
	v_lshlrev_b32_e32 v0, 2, v20
	s_sub_i32 s16, s20, s16
	s_and_b32 s18, s17, 0xffffff80
	v_add_u32_e32 v23, 32, v22
	s_waitcnt vmcnt(0)
	v_add_u32_e32 v24, 64, v22
	v_add_u32_e32 v25, 0x60, v22
	v_and_b32_e32 v2, 60, v0
	s_sext_i32_i16 s16, s16
	v_add_u32_e32 v0, s18, v22
	v_add_u32_e32 v6, s18, v23
	v_add_u32_e32 v12, s18, v24
	v_add_u32_e32 v14, s18, v25
	s_lshl_b32 s16, s16, 6
	v_ashrrev_i32_e32 v1, 31, v0
	v_ashrrev_i32_e32 v7, 31, v6
	v_ashrrev_i32_e32 v13, 31, v12
	v_ashrrev_i32_e32 v15, 31, v14
	s_ashr_i32 s17, s16, 31
	v_lshlrev_b64 v[0:1], 13, v[0:1]
	v_lshlrev_b64 v[6:7], 13, v[6:7]
	v_lshlrev_b64 v[12:13], 13, v[12:13]
	v_lshlrev_b64 v[14:15], 13, v[14:15]
	s_waitcnt lgkmcnt(0)
	v_lshl_add_u64 v[0:1], s[14:15], 0, v[0:1]
	s_lshl_b64 s[16:17], s[16:17], 2
	v_lshl_add_u64 v[6:7], s[14:15], 0, v[6:7]
	v_lshl_add_u64 v[12:13], s[14:15], 0, v[12:13]
	v_lshl_add_u64 v[14:15], s[14:15], 0, v[14:15]
	v_lshl_add_u64 v[4:5], v[0:1], 0, s[16:17]
	v_lshlrev_b32_e32 v0, 2, v2
	v_mov_b32_e32 v1, v3
	v_lshl_add_u64 v[6:7], v[6:7], 0, s[16:17]
	v_lshl_add_u64 v[12:13], v[12:13], 0, s[16:17]
	v_lshl_add_u64 v[14:15], v[14:15], 0, s[16:17]
	v_lshl_add_u64 v[4:5], v[4:5], 0, v[0:1]
	v_lshl_add_u64 v[8:9], v[6:7], 0, v[0:1]
	v_lshl_add_u64 v[12:13], v[12:13], 0, v[0:1]
	v_lshl_add_u64 v[16:17], v[14:15], 0, v[0:1]
	global_load_dwordx4 v[4:7], v[4:5], off
	s_nop 0
	global_load_dwordx4 v[8:11], v[8:9], off
	s_nop 0
	global_load_dwordx4 v[12:15], v[12:13], off
	s_nop 0
	global_load_dwordx4 v[16:19], v[16:17], off
	v_lshlrev_b32_e32 v20, 4, v20
	v_and_b32_e32 v28, 0x70, v20
	v_ashrrev_i32_e32 v1, 3, v21
	v_mul_u32_u24_e32 v26, 0x104, v28
	v_mul_lo_u32 v27, v22, s87
	s_lshl_b32 s23, s20, 6
	s_lshl_b32 s21, s3, 6
	s_mov_b32 s22, 0
	v_lshlrev_b32_e32 v20, 2, v2
	v_lshlrev_b32_e32 v2, 1, v28
	s_mov_b32 s26, s20
	s_waitcnt vmcnt(0)
	s_branch .LBB0_197

; #define LAS __attribute__((address_space(3)))
; __device__ __forceinline__ int opaque_tid(int wv) { asm volatile("" : "+s"(wv)); unsigned z = 0u; asm volatile("" : "+v"(z)); const int l = __builtin_amdgcn_mbcnt_hi(~0u, __builtin_amdgcn_mbcnt_lo(~0u, z)); return (wv << 6) | l; }
; __device__ __forceinline__ void convert_weight(int wv, const float* __restrict__ src, int ldsrc, int Ksrc, bf16_t* dst, int ldd, int koff, int ntn, const float* kscale, int mode, LAS float* tile, int pidx, int pcnt) {
;     const int tid = opaque_tid(wv); const int ntk = Ksrc / 128; const int total = ntn * ntk; const int G = pcnt;
;     const int kk0 = tid >> 4, n4 = (tid & 15) * 4;
;     f32x4 v[4]; float ks[4];
;     auto prefetch = [&](int t) {
;         const int tn = t % ntn, tk = t / ntn; const int n0 = tn * 64, k0 = tk * 128;
;         int scol = n0, nvalid = 64;
;         if (mode == 1) { if (n0 < 5632) scol = n0; else if (n0 < 13312) scol = n0 + 8; else if (n0 == 13312) { scol = 5632; nvalid = 8; } else { scol = 0; nvalid = 0; } }
; #pragma unroll
;         for (int i = 0; i < 4; ++i) { const int kk = kk0 + i * 32; v[i] = (f32x4){0.f, 0.f, 0.f, 0.f};
;             if (n4 < nvalid) v[i] = *(const f32x4*)(src + (size_t)(k0 + kk) * ldsrc + scol + n4);
;             ks[i] = kscale ? kscale[k0 + kk] : 1.0f; }
;     };
;     int t = pidx; int buf = 0;
;     if (t < total) prefetch(t);
; __device__ __forceinline__ void convert_layer(int wv, PP P, int L, int mask, LAS float* tile, int pidx, int pcnt) {
;     ...
;         convert_weight(wv, P->w_br_m + (size_t)L * 1024 * D, D, 1024, wbr, D, 512, D / 64, nullptr, 0, tile, pidx, pcnt);
.LBB0_201:
	s_mov_b32 s14, s95
	v_mov_b32_e32 v0, v3
	s_cmpk_gt_i32 s20, 0xff
	s_waitcnt vmcnt(0) lgkmcnt(0)
	s_barrier
	s_cbranch_scc1 .LBB0_208
	v_mbcnt_lo_u32_b32 v0, -1, v0
	v_mbcnt_hi_u32_b32 v20, -1, v0
	v_lshl_or_b32 v21, s14, 6, v20
	s_ashr_i32 s14, s20, 31
	s_lshr_b32 s14, s14, 27
	s_add_i32 s15, s20, s14
	s_load_dwordx2 s[12:13], s[4:5], 0x50
	s_waitcnt lgkmcnt(0)
	s_mul_i32 s98, s2, 0x800000
	s_add_u32 s12, s12, s98
	s_addc_u32 s13, s13, 0
	v_ashrrev_i32_e32 v22, 4, v21
	s_and_b32 s14, s15, 0x3ffffe0
	s_lshl_b32 s15, s15, 2
	v_lshlrev_b32_e32 v0, 2, v20
	s_and_b32 s16, s15, 0xffffff80
	v_add_u32_e32 v23, 32, v22
	v_add_u32_e32 v24, 64, v22
	v_add_u32_e32 v25, 0x60, v22
	v_and_b32_e32 v2, 60, v0
	s_sub_i32 s14, s20, s14
	v_add_u32_e32 v0, s16, v22
	v_add_u32_e32 v6, s16, v23
	v_add_u32_e32 v12, s16, v24
	v_add_u32_e32 v14, s16, v25
	s_lshl_b32 s14, s14, 6
	v_ashrrev_i32_e32 v1, 31, v0
	v_ashrrev_i32_e32 v7, 31, v6
	v_ashrrev_i32_e32 v13, 31, v12
	v_ashrrev_i32_e32 v15, 31, v14
	s_ashr_i32 s15, s14, 31
	v_lshlrev_b64 v[0:1], 13, v[0:1]
	v_lshlrev_b64 v[6:7], 13, v[6:7]
	v_lshlrev_b64 v[12:13], 13, v[12:13]
	v_lshlrev_b64 v[14:15], 13, v[14:15]
	s_waitcnt lgkmcnt(0)
	v_lshl_add_u64 v[0:1], s[12:13], 0, v[0:1]
	s_lshl_b64 s[14:15], s[14:15], 2
	v_lshl_add_u64 v[6:7], s[12:13], 0, v[6:7]
	v_lshl_add_u64 v[12:13], s[12:13], 0, v[12:13]
	v_lshl_add_u64 v[14:15], s[12:13], 0, v[14:15]
	v_lshl_add_u64 v[4:5], v[0:1], 0, s[14:15]
	v_lshlrev_b32_e32 v0, 2, v2
	v_mov_b32_e32 v1, v3
	v_lshl_add_u64 v[6:7], v[6:7], 0, s[14:15]
	v_lshl_add_u64 v[12:13], v[12:13], 0, s[14:15]
	v_lshl_add_u64 v[14:15], v[14:15], 0, s[14:15]
	v_lshl_add_u64 v[4:5], v[4:5], 0, v[0:1]
	v_lshl_add_u64 v[8:9], v[6:7], 0, v[0:1]
	v_lshl_add_u64 v[12:13], v[12:13], 0, v[0:1]
	v_lshl_add_u64 v[16:17], v[14:15], 0, v[0:1]
	global_load_dwordx4 v[4:7], v[4:5], off
	s_nop 0
	global_load_dwordx4 v[8:11], v[8:9], off
	s_nop 0
	global_load_dwordx4 v[12:15], v[12:13], off
	s_nop 0
	global_load_dwordx4 v[16:19], v[16:17], off
	v_lshlrev_b32_e32 v20, 4, v20
	v_and_b32_e32 v28, 0x70, v20
	s_add_u32 s14, s6, 0x4200400
	v_ashrrev_i32_e32 v1, 3, v21
	v_mul_u32_u24_e32 v26, 0x104, v28
	s_addc_u32 s15, s7, 0
	v_mul_lo_u32 v27, v22, s87
	s_lshl_b32 s23, s20, 6
	s_lshl_b32 s21, s3, 6
	s_mov_b32 s22, 0
	v_lshlrev_b32_e32 v20, 2, v2
	v_lshlrev_b32_e32 v2, 1, v28
	s_mov_b32 s26, s20
	s_waitcnt vmcnt(0)
	s_branch .LBB0_204

; #define LAS __attribute__((address_space(3)))
; __device__ __forceinline__ int opaque_tid(int wv) { asm volatile("" : "+s"(wv)); unsigned z = 0u; asm volatile("" : "+v"(z)); const int l = __builtin_amdgcn_mbcnt_hi(~0u, __builtin_amdgcn_mbcnt_lo(~0u, z)); return (wv << 6) | l; }
; __device__ __forceinline__ void convert_weight(int wv, const float* __restrict__ src, int ldsrc, int Ksrc, bf16_t* dst, int ldd, int koff, int ntn, const float* kscale, int mode, LAS float* tile, int pidx, int pcnt) {
;     const int tid = opaque_tid(wv); const int ntk = Ksrc / 128; const int total = ntn * ntk; const int G = pcnt;
;     const int kk0 = tid >> 4, n4 = (tid & 15) * 4;
;     f32x4 v[4]; float ks[4];
;     auto prefetch = [&](int t) {
;         const int tn = t % ntn, tk = t / ntn; const int n0 = tn * 64, k0 = tk * 128;
;         int scol = n0, nvalid = 64;
;         if (mode == 1) { if (n0 < 5632) scol = n0; else if (n0 < 13312) scol = n0 + 8; else if (n0 == 13312) { scol = 5632; nvalid = 8; } else { scol = 0; nvalid = 0; } }
; #pragma unroll
;         for (int i = 0; i < 4; ++i) { const int kk = kk0 + i * 32; v[i] = (f32x4){0.f, 0.f, 0.f, 0.f};
;             if (n4 < nvalid) v[i] = *(const f32x4*)(src + (size_t)(k0 + kk) * ldsrc + scol + n4);
;             ks[i] = kscale ? kscale[k0 + kk] : 1.0f; }
;     };
;     int t = pidx; int buf = 0;
;     if (t < total) prefetch(t);
; __device__ __forceinline__ void convert_layer(int wv, PP P, int L, int mask, LAS float* tile, int pidx, int pcnt) {
;     ...
;         convert_weight(wv, P->w_br_d + (size_t)L * 512 * D, D, 512, wbr, D, 1536, D / 64, nullptr, 0, tile, pidx, pcnt);
.LBB0_208:
	s_mov_b32 s12, s95
	v_mov_b32_e32 v0, v3
	s_andn2_b64 vcc, exec, s[8:9]
	s_barrier
	s_cbranch_vccnz .LBB0_215
	v_mbcnt_lo_u32_b32 v0, -1, v0
	v_mbcnt_hi_u32_b32 v20, -1, v0
	v_lshl_or_b32 v21, s12, 6, v20
	s_ashr_i32 s12, s20, 31
	s_lshr_b32 s12, s12, 27
	s_add_i32 s13, s20, s12
	s_load_dwordx2 s[8:9], s[4:5], 0x58
	s_waitcnt lgkmcnt(0)
	s_mul_i32 s98, s2, 0x400000
	s_add_u32 s8, s8, s98
	s_addc_u32 s9, s9, 0
	v_ashrrev_i32_e32 v22, 4, v21
	s_and_b32 s12, s13, 0x3ffffe0
	s_lshl_b32 s13, s13, 2
	v_lshlrev_b32_e32 v0, 2, v20
	s_and_b32 s14, s13, 0xffffff80
	v_add_u32_e32 v23, 32, v22
	v_add_u32_e32 v24, 64, v22
	v_add_u32_e32 v25, 0x60, v22
	v_and_b32_e32 v2, 60, v0
	s_sub_i32 s12, s20, s12
	v_add_u32_e32 v0, s14, v22
	s_waitcnt vmcnt(5)
	v_add_u32_e32 v6, s14, v23
	s_waitcnt vmcnt(3)
	v_add_u32_e32 v12, s14, v24
	v_add_u32_e32 v14, s14, v25
	s_lshl_b32 s12, s12, 6
	v_ashrrev_i32_e32 v1, 31, v0
	v_ashrrev_i32_e32 v7, 31, v6
	v_ashrrev_i32_e32 v13, 31, v12
	v_ashrrev_i32_e32 v15, 31, v14
	s_ashr_i32 s13, s12, 31
	v_lshlrev_b64 v[0:1], 13, v[0:1]
	v_lshlrev_b64 v[6:7], 13, v[6:7]
	v_lshlrev_b64 v[12:13], 13, v[12:13]
	v_lshlrev_b64 v[14:15], 13, v[14:15]
	s_waitcnt lgkmcnt(0)
	v_lshl_add_u64 v[0:1], s[8:9], 0, v[0:1]
	s_lshl_b64 s[12:13], s[12:13], 2
	v_lshl_add_u64 v[6:7], s[8:9], 0, v[6:7]
	v_lshl_add_u64 v[12:13], s[8:9], 0, v[12:13]
	v_lshl_add_u64 v[14:15], s[8:9], 0, v[14:15]
	v_lshl_add_u64 v[4:5], v[0:1], 0, s[12:13]
	v_lshlrev_b32_e32 v0, 2, v2
	v_mov_b32_e32 v1, v3
	v_lshl_add_u64 v[6:7], v[6:7], 0, s[12:13]
	v_lshl_add_u64 v[12:13], v[12:13], 0, s[12:13]
	v_lshl_add_u64 v[14:15], v[14:15], 0, s[12:13]
	v_lshl_add_u64 v[4:5], v[4:5], 0, v[0:1]
	v_lshl_add_u64 v[8:9], v[6:7], 0, v[0:1]
	v_lshl_add_u64 v[12:13], v[12:13], 0, v[0:1]
	s_waitcnt vmcnt(2)
	v_lshl_add_u64 v[16:17], v[14:15], 0, v[0:1]
	global_load_dwordx4 v[4:7], v[4:5], off
	s_nop 0
	global_load_dwordx4 v[8:11], v[8:9], off
	s_nop 0
	global_load_dwordx4 v[12:15], v[12:13], off
	s_nop 0
	global_load_dwordx4 v[16:19], v[16:17], off
	v_lshlrev_b32_e32 v20, 4, v20
	v_and_b32_e32 v28, 0x70, v20
	s_add_u32 s12, s6, 0x4200c00
	v_ashrrev_i32_e32 v1, 3, v21
	v_mul_u32_u24_e32 v26, 0x104, v28
	s_addc_u32 s13, s7, 0
	v_mul_lo_u32 v27, v22, s87
	s_lshl_b32 s21, s20, 6
	s_lshl_b32 s18, s3, 6
	s_mov_b32 s19, 0
	v_lshlrev_b32_e32 v20, 2, v2
	v_lshlrev_b32_e32 v2, 1, v28
	s_mov_b32 s24, s20
	s_waitcnt vmcnt(0)
	s_branch .LBB0_211

; #define LAS __attribute__((address_space(3)))
; __device__ __forceinline__ int opaque_tid(int wv) { asm volatile("" : "+s"(wv)); unsigned z = 0u; asm volatile("" : "+v"(z)); const int l = __builtin_amdgcn_mbcnt_hi(~0u, __builtin_amdgcn_mbcnt_lo(~0u, z)); return (wv << 6) | l; }
; __device__ __forceinline__ void convert_weight(int wv, const float* __restrict__ src, int ldsrc, int Ksrc, bf16_t* dst, int ldd, int koff, int ntn, const float* kscale, int mode, LAS float* tile, int pidx, int pcnt) {
;     const int tid = opaque_tid(wv); const int ntk = Ksrc / 128; const int total = ntn * ntk; const int G = pcnt;
;     const int kk0 = tid >> 4, n4 = (tid & 15) * 4;
;     f32x4 v[4]; float ks[4];
;     auto prefetch = [&](int t) {
;         const int tn = t % ntn, tk = t / ntn; const int n0 = tn * 64, k0 = tk * 128;
;         int scol = n0, nvalid = 64;
;         if (mode == 1) { if (n0 < 5632) scol = n0; else if (n0 < 13312) scol = n0 + 8; else if (n0 == 13312) { scol = 5632; nvalid = 8; } else { scol = 0; nvalid = 0; } }
; #pragma unroll
;         for (int i = 0; i < 4; ++i) { const int kk = kk0 + i * 32; v[i] = (f32x4){0.f, 0.f, 0.f, 0.f};
;             if (n4 < nvalid) v[i] = *(const f32x4*)(src + (size_t)(k0 + kk) * ldsrc + scol + n4);
;             ks[i] = kscale ? kscale[k0 + kk] : 1.0f; }
;     };
;     int t = pidx; int buf = 0;
;     if (t < total) prefetch(t);
; __device__ __forceinline__ void convert_layer(int wv, PP P, int L, int mask, LAS float* tile, int pidx, int pcnt) {
;     ...
;     if (mask & 4) convert_weight(wv, P->w_out + (size_t)L * D * D, D, D, (bf16_t*)(dob + DO_WOUT), D, 0, D / 64, nullptr, 0, tile, pidx, pcnt);
.LBB0_215:
	s_mov_b32 s8, s95
	v_mov_b32_e32 v0, v3
	s_cmpk_gt_i32 s20, 0x1ff
	s_barrier
	s_cbranch_scc1 .LBB0_222
	v_mbcnt_lo_u32_b32 v0, -1, v0
	s_add_u32 s6, s6, 0x4a00000
	v_mbcnt_hi_u32_b32 v20, -1, v0
	s_addc_u32 s7, s7, 0
	v_lshl_or_b32 v21, s8, 6, v20
	s_ashr_i32 s8, s20, 31
	s_lshr_b32 s8, s8, 27
	s_add_i32 s9, s20, s8
	s_load_dwordx2 s[4:5], s[4:5], 0x60
	s_waitcnt lgkmcnt(0)
	s_mul_i32 s98, s2, 0x1000000
	s_add_u32 s4, s4, s98
	s_addc_u32 s5, s5, 0
	v_ashrrev_i32_e32 v22, 4, v21
	s_and_b32 s8, s9, 0x3ffffe0
	s_lshl_b32 s9, s9, 2
	v_lshlrev_b32_e32 v0, 2, v20
	s_and_b32 s12, s9, 0xffffff80
	v_add_u32_e32 v23, 32, v22
	v_add_u32_e32 v24, 64, v22
	v_add_u32_e32 v25, 0x60, v22
	v_and_b32_e32 v2, 60, v0
	s_sub_i32 s8, s20, s8
	v_add_u32_e32 v0, s12, v22
	s_waitcnt vmcnt(5)
	v_add_u32_e32 v6, s12, v23
	s_waitcnt vmcnt(3)
	v_add_u32_e32 v12, s12, v24
	v_add_u32_e32 v14, s12, v25
	s_lshl_b32 s8, s8, 6
	v_ashrrev_i32_e32 v1, 31, v0
	v_ashrrev_i32_e32 v7, 31, v6
	v_ashrrev_i32_e32 v13, 31, v12
	v_ashrrev_i32_e32 v15, 31, v14
	s_ashr_i32 s9, s8, 31
	v_lshlrev_b64 v[0:1], 13, v[0:1]
	v_lshlrev_b64 v[6:7], 13, v[6:7]
	v_lshlrev_b64 v[12:13], 13, v[12:13]
	v_lshlrev_b64 v[14:15], 13, v[14:15]
	s_waitcnt lgkmcnt(0)
	v_lshl_add_u64 v[0:1], s[4:5], 0, v[0:1]
	s_lshl_b64 s[8:9], s[8:9], 2
	v_lshl_add_u64 v[6:7], s[4:5], 0, v[6:7]
	v_lshl_add_u64 v[12:13], s[4:5], 0, v[12:13]
	v_lshl_add_u64 v[14:15], s[4:5], 0, v[14:15]
	v_lshl_add_u64 v[4:5], v[0:1], 0, s[8:9]
	v_lshlrev_b32_e32 v0, 2, v2
	v_mov_b32_e32 v1, v3
	v_lshl_add_u64 v[6:7], v[6:7], 0, s[8:9]
	v_lshl_add_u64 v[12:13], v[12:13], 0, s[8:9]
	v_lshl_add_u64 v[14:15], v[14:15], 0, s[8:9]
	v_lshl_add_u64 v[4:5], v[4:5], 0, v[0:1]
	v_lshl_add_u64 v[8:9], v[6:7], 0, v[0:1]
	v_lshl_add_u64 v[12:13], v[12:13], 0, v[0:1]
	s_waitcnt vmcnt(2)
	v_lshl_add_u64 v[16:17], v[14:15], 0, v[0:1]
	global_load_dwordx4 v[4:7], v[4:5], off
	s_nop 0
	global_load_dwordx4 v[8:11], v[8:9], off
	s_nop 0
	global_load_dwordx4 v[12:15], v[12:13], off
	s_nop 0
	global_load_dwordx4 v[16:19], v[16:17], off
	v_lshlrev_b32_e32 v20, 4, v20
	v_and_b32_e32 v28, 0x70, v20
	v_ashrrev_i32_e32 v1, 3, v21
	v_mul_u32_u24_e32 v26, 0x104, v28
	v_mul_lo_u32 v27, v22, s87
	s_lshl_b32 s16, s20, 6
	s_lshl_b32 s14, s3, 6
	s_mov_b32 s15, 0
	v_lshlrev_b32_e32 v20, 2, v2
	v_lshlrev_b32_e32 v2, 1, v28
	s_waitcnt vmcnt(0)
	s_branch .LBB0_218

; #define LAS __attribute__((address_space(3)))
; __device__ __forceinline__ float shx(float v, int mask, int lane) { return __int_as_float(__builtin_amdgcn_ds_bpermute((lane ^ mask) << 2, __float_as_int(v))); }
; __device__ __forceinline__ unsigned pack2(float lo, float hi) { unsigned r; asm("v_cvt_pk_bf16_f32 %0, %1, %2" : "=v"(r) : "v"(lo), "v"(hi)); return r; }
; __device__ __forceinline__ void attn_phase(int wv, PP P, int L, LAS unsigned char* lds) {
;     ...
;             if (kt <= my_last) {
;                 bf16x8 pf[2][2];
; #pragma unroll
;                 for (int m = 0; m < 2; ++m) {
;                     f32x4 sa[4];
; #pragma unroll
;                     for (int nt = 0; nt < 4; ++nt) { sa[nt] = (f32x4){0.f, 0.f, 0.f, 0.f};
; #pragma unroll
;                         for (int kk = 0; kk < 2; ++kk) { const bf16x8 kf = *(const LAS bf16x8*)(lds + kbuf + (nt * 16 + fr) * 272 + (m * 64 + kk * 32 + fq * 8) * 2);
;                             sa[nt] = __builtin_amdgcn_mfma_f32_16x16x32_bf16(kf, qf[m][kk], sa[nt], 0, 0, 0); } }
;                     float mx = -INFINITY;
; #pragma unroll
;                     for (int nt = 0; nt < 4; ++nt)
; #pragma unroll
;                         for (int q = 0; q < 4; ++q) { const bool kv = (kt > 0) || (nt * 16 + fq * 4 + q >= 48); sa[nt][q] = kv ? sa[nt][q] * 0.125f : -INFINITY; mx = fmaxf(mx, sa[nt][q]); }
;                     mx = fmaxf(mx, shx(mx, 16, lane)); mx = fmaxf(mx, shx(mx, 32, lane));
;                     const float mnew = fmaxf(mrun[m], mx); const float alpha = __expf(mrun[m] - mnew); mrun[m] = mnew;
;                     float rsum = 0.f;
; #pragma unroll
;                     for (int nt = 0; nt < 4; ++nt)
; #pragma unroll
;                         for (int q = 0; q < 4; ++q) { sa[nt][q] = __expf(sa[nt][q] - mnew); rsum += sa[nt][q]; }
;                     rsum += shx(rsum, 16, lane); rsum += shx(rsum, 32, lane);
;                     lrun[m] = lrun[m] * alpha + rsum;
; #pragma unroll
;                     for (int e = 0; e < 8; ++e) O[m][e] *= alpha;
; #pragma unroll
;                     for (int kp = 0; kp < 2; ++kp) { u32x4 t; t.x = pack2(sa[2 * kp][0], sa[2 * kp][1]); t.y = pack2(sa[2 * kp][2], sa[2 * kp][3]); t.z = pack2(sa[2 * kp + 1][0], sa[2 * kp + 1][1]); t.w = pack2(sa[2 * kp + 1][2], sa[2 * kp + 1][3]);
;                         pf[m][kp] = __builtin_bit_cast(bf16x8, t); }
.LBB0_365:
	s_and_b64 s[26:27], s[6:7], s[18:19]
	v_cndmask_b32_e64 v36, 0, 1, s[26:27]
	s_lshl_b32 s24, s24, 1
	v_readfirstlane_b32 s9, v36
	s_sub_i32 s9, s24, s9
	s_and_b64 s[26:27], s[4:5], exec
	s_cselect_b32 s25, s9, -1
	s_cmp_lt_i32 s25, 0
	s_cbranch_scc1 .LBB0_367
	ds_read_b128 v[36:39], v171 offset:13056
	ds_read_b128 v[40:43], v171 offset:13120
	s_waitcnt vmcnt(1) lgkmcnt(1)
	v_mfma_f32_16x16x32_bf16 v[36:39], v[36:39], v[12:15], 0
	ds_read_b128 v[44:47], v171 offset:13248
	s_waitcnt lgkmcnt(1)
	v_mfma_f32_16x16x32_bf16 v[36:39], v[40:43], v[4:7], v[36:39]
	s_nop 7
	v_mul_f32_e32 v40, 0x3e000000, v36
	v_mul_f32_e32 v41, 0x3e000000, v37
	v_max3_f32 v40, v40, s52, v41
	v_mul_f32_e32 v41, 0x3e000000, v38
	v_mul_f32_e32 v42, 0x3e000000, v39
	v_max3_f32 v40, v40, v41, v42
	v_mov_b32_e32 v41, v40
	s_nop 1
	v_permlane16_swap_b32_e32 v40, v41
	s_waitcnt lgkmcnt(0)
	v_max_f32_e32 v41, v41, v41
	v_max_f32_e32 v40, v40, v41
	v_mov_b32_e32 v41, v40
	s_nop 1
	v_permlane32_swap_b32_e32 v40, v41
	s_waitcnt lgkmcnt(0)
	v_max3_f32 v96, v40, v41, s52
	v_fma_f32 v36, v36, s50, -v96
	v_mul_f32_e32 v36, 0x3fb8aa3b, v36
	v_exp_f32_e32 v53, v36
	v_fma_f32 v36, v37, s50, -v96
	v_mul_f32_e32 v36, 0x3fb8aa3b, v36
	v_exp_f32_e32 v57, v36
	v_fma_f32 v36, v38, s50, -v96
	v_mul_f32_e32 v36, 0x3fb8aa3b, v36
	v_sub_f32_e32 v40, 0xff800000, v96
	v_exp_f32_e32 v55, v36
	v_fma_f32 v36, v39, s50, -v96
	v_mul_f32_e32 v40, 0x3fb8aa3b, v40
	v_mul_f32_e32 v36, 0x3fb8aa3b, v36
	v_exp_f32_e32 v49, v40
	v_exp_f32_e32 v59, v36
	v_cvt_pk_bf16_f32 v36, v49, v49
	v_cvt_pk_bf16_f32 v40, v53, v57
	s_nop 0
	v_mov_b32_e32 v38, v36
	v_mov_b32_e32 v39, v36
	v_mov_b32_e32 v37, v36
	v_mov_b64_e32 v[66:67], v[38:39]
	v_mov_b32_e32 v66, v40
	ds_read_b128 v[40:43], v171 offset:13184
	s_waitcnt lgkmcnt(0)
	v_mfma_f32_16x16x32_bf16 v[40:43], v[40:43], v[8:11], 0
	v_cvt_pk_bf16_f32 v67, v55, v59
	v_mov_b64_e32 v[64:65], v[36:37]
	s_waitcnt vmcnt(0)
	v_mfma_f32_16x16x32_bf16 v[40:43], v[44:47], v[16:19], v[40:43]
	s_nop 7
	v_mul_f32_e32 v44, 0x3e000000, v40
	v_mul_f32_e32 v45, 0x3e000000, v41
	v_max3_f32 v44, v44, s52, v45
	v_mul_f32_e32 v45, 0x3e000000, v42
	v_mul_f32_e32 v46, 0x3e000000, v43
	v_max3_f32 v44, v44, v45, v46
	v_mov_b32_e32 v45, v44
	s_nop 1
	v_permlane16_swap_b32_e32 v44, v45
	s_waitcnt lgkmcnt(0)
	v_max_f32_e32 v45, v45, v45
	v_max_f32_e32 v44, v44, v45
	v_mov_b32_e32 v45, v44
	s_nop 1
	v_permlane32_swap_b32_e32 v44, v45
	s_waitcnt lgkmcnt(0)
	v_max3_f32 v117, v44, v45, s52
	v_sub_f32_e32 v44, 0xff800000, v117
	v_mul_f32_e32 v44, 0x3fb8aa3b, v44
	v_exp_f32_e32 v48, v44
	v_fma_f32 v40, v40, s50, -v117
	v_mul_f32_e32 v40, 0x3fb8aa3b, v40
	v_exp_f32_e32 v52, v40
	v_pk_add_f32 v[44:45], v[48:49], 0 op_sel_hi:[1,0]
	v_fma_f32 v40, v41, s50, -v117
	v_pk_add_f32 v[44:45], v[48:49], v[44:45]
	v_mul_f32_e32 v40, 0x3fb8aa3b, v40
	v_pk_add_f32 v[44:45], v[48:49], v[44:45]
	v_exp_f32_e32 v56, v40
	v_pk_add_f32 v[44:45], v[48:49], v[44:45]
	v_fma_f32 v40, v42, s50, -v117
	v_pk_add_f32 v[44:45], v[48:49], v[44:45]
	v_mul_f32_e32 v40, 0x3fb8aa3b, v40
	v_pk_add_f32 v[44:45], v[48:49], v[44:45]
	v_exp_f32_e32 v54, v40
	v_pk_add_f32 v[44:45], v[48:49], v[44:45]
	v_fma_f32 v40, v43, s50, -v117
	v_pk_add_f32 v[44:45], v[48:49], v[44:45]
	v_mul_f32_e32 v40, 0x3fb8aa3b, v40
	v_pk_add_f32 v[44:45], v[48:49], v[44:45]
	v_exp_f32_e32 v58, v40
	v_pk_add_f32 v[40:41], v[48:49], v[44:45]
	s_nop 0
	v_pk_add_f32 v[40:41], v[48:49], v[40:41]
	s_nop 0
	v_pk_add_f32 v[40:41], v[48:49], v[40:41]
	s_nop 0
	v_pk_add_f32 v[40:41], v[52:53], v[40:41]
	v_cvt_pk_bf16_f32 v52, v52, v56
	s_nop 0
	v_pk_add_f32 v[40:41], v[56:57], v[40:41]
	s_nop 0
	v_pk_add_f32 v[40:41], v[54:55], v[40:41]
	s_nop 0
	v_pk_add_f32 v[40:41], v[58:59], v[40:41]
	v_mov_b32_e32 v43, v41
	v_mov_b32_e32 v42, v40
	s_nop 0
	v_permlane16_swap_b32_e32 v41, v43
	v_permlane16_swap_b32_e32 v40, v42
	s_waitcnt lgkmcnt(0)
	v_pk_add_f32 v[40:41], v[40:41], v[42:43]
	v_mov_b32_e32 v43, v41
	v_mov_b32_e32 v42, v40
	s_nop 0
	v_permlane32_swap_b32_e32 v41, v43
	v_permlane32_swap_b32_e32 v40, v42
	s_waitcnt lgkmcnt(0)
; __device__ __forceinline__ u32x2 trr(unsigned addr) { u32x2 r; asm volatile("ds_read_b64_tr_b16 %0, %1" : "=&v"(r) : "v"(addr) : "memory"); return r; }
; __device__ __forceinline__ void trw4(u32x2& a, u32x2& b, u32x2& c, u32x2& d) { asm volatile("s_waitcnt lgkmcnt(0)" : "+v"(a), "+v"(b), "+v"(c), "+v"(d) : : "memory"); }
; __device__ __forceinline__ unsigned pack2(float lo, float hi) { unsigned r; asm("v_cvt_pk_bf16_f32 %0, %1, %2" : "=v"(r) : "v"(lo), "v"(hi)); return r; }
; __device__ __forceinline__ void attn_phase(int wv, PP P, int L, LAS unsigned char* lds) {
;     ...
; #pragma unroll
;                     for (int e = 0; e < 8; ++e) O[m][e] *= alpha;
; #pragma unroll
;                     for (int kp = 0; kp < 2; ++kp) { u32x4 t; t.x = pack2(sa[2 * kp][0], sa[2 * kp][1]); t.y = pack2(sa[2 * kp][2], sa[2 * kp][3]); t.z = pack2(sa[2 * kp + 1][0], sa[2 * kp + 1][1]); t.w = pack2(sa[2 * kp + 1][2], sa[2 * kp + 1][3]);
;                         pf[m][kp] = __builtin_bit_cast(bf16x8, t); }
;                 }
;                 const unsigned trv = ldsb + vbuf + (4 * fq + trq) * 272 + (4 * trp) * 2;
; #pragma unroll
;                 for (int kp = 0; kp < 2; ++kp) {
;                     u32x2 vl[8], vh[8];
; #pragma unroll
;                     for (int e = 0; e < 8; ++e) { vl[e] = trr(trv + (32 * kp) * 272 + e * 32); vh[e] = trr(trv + (32 * kp + 16) * 272 + e * 32); }
;                     trw4(vl[0], vl[1], vl[2], vl[3]); trw4(vl[4], vl[5], vl[6], vl[7]); trw4(vh[0], vh[1], vh[2], vh[3]); trw4(vh[4], vh[5], vh[6], vh[7]);
; #pragma unroll
;                     for (int e = 0; e < 8; ++e) { const bf16x8 vf = mk8(vl[e], vh[e]);
;                         O[0][e] = __builtin_amdgcn_mfma_f32_16x16x32_bf16(vf, pf[0][kp], O[0][e], 0, 0, 0);
;                         O[1][e] = __builtin_amdgcn_mfma_f32_16x16x32_bf16(vf, pf[1][kp], O[1][e], 0, 0, 0); }
;                 }
	v_pk_add_f32 v[42:43], v[40:41], v[42:43]
	v_pk_mul_f32 v[40:41], v[48:49], 0 op_sel_hi:[1,0]
	v_pk_fma_f32 v[134:135], v[48:49], 0, v[42:43] op_sel_hi:[1,0,1]
	v_cvt_pk_bf16_f32 v48, v48, v48
	v_mov_b32_e32 v44, v41
	v_mov_b32_e32 v50, v48
	v_mov_b32_e32 v51, v48
	v_mov_b32_e32 v49, v48
	v_mov_b64_e32 v[94:95], v[50:51]
	v_mov_b32_e32 v94, v52
	ds_read_b64_tr_b16 v[52:53], v172
	v_cvt_pk_bf16_f32 v95, v54, v58
	ds_read_b64_tr_b16 v[54:55], v173
	ds_read_b64_tr_b16 v[56:57], v174
	ds_read_b64_tr_b16 v[58:59], v175
	ds_read_b64_tr_b16 v[60:61], v176
	ds_read_b64_tr_b16 v[62:63], v177
	ds_read_b64_tr_b16 v[68:69], v178
	ds_read_b64_tr_b16 v[70:71], v179
	ds_read_b64_tr_b16 v[72:73], v180
	ds_read_b64_tr_b16 v[74:75], v181
	ds_read_b64_tr_b16 v[76:77], v182
	ds_read_b64_tr_b16 v[78:79], v183
	ds_read_b64_tr_b16 v[80:81], v184
	ds_read_b64_tr_b16 v[82:83], v185
	ds_read_b64_tr_b16 v[84:85], v186
	ds_read_b64_tr_b16 v[86:87], v187
	s_nop 0
	s_waitcnt lgkmcnt(0)
	v_mov_b32_e32 v45, v41
	s_waitcnt lgkmcnt(0)
	s_waitcnt lgkmcnt(0)
	v_mov_b32_e32 v46, v41
	v_mov_b32_e32 v47, v41
	s_waitcnt lgkmcnt(0)
	v_mov_b32_e32 v41, v40
	v_mov_b32_e32 v42, v40
	v_mfma_f32_16x16x32_bf16 v[88:91], v[52:55], v[36:39], v[44:47]
	v_mov_b32_e32 v43, v40
	v_mov_b64_e32 v[92:93], v[48:49]
	v_mfma_f32_16x16x32_bf16 v[98:101], v[56:59], v[36:39], v[44:47]
	v_mfma_f32_16x16x32_bf16 v[102:105], v[60:63], v[36:39], v[44:47]
	v_mfma_f32_16x16x32_bf16 v[106:109], v[68:71], v[36:39], v[44:47]
	v_mfma_f32_16x16x32_bf16 v[110:113], v[72:75], v[36:39], v[44:47]
	v_mfma_f32_16x16x32_bf16 v[136:139], v[76:79], v[36:39], v[44:47]
	v_mfma_f32_16x16x32_bf16 v[144:147], v[80:83], v[36:39], v[44:47]
	v_mfma_f32_16x16x32_bf16 v[152:155], v[84:87], v[36:39], v[44:47]
	ds_read_b64_tr_b16 v[36:37], v188
	ds_read_b64_tr_b16 v[38:39], v189
	v_mfma_f32_16x16x32_bf16 v[52:55], v[52:55], v[48:51], v[40:43]
	v_mfma_f32_16x16x32_bf16 v[56:59], v[56:59], v[48:51], v[40:43]
	v_mfma_f32_16x16x32_bf16 v[60:63], v[60:63], v[48:51], v[40:43]
	v_mfma_f32_16x16x32_bf16 v[68:71], v[68:71], v[48:51], v[40:43]
	v_mfma_f32_16x16x32_bf16 v[118:121], v[72:75], v[48:51], v[40:43]
	v_mfma_f32_16x16x32_bf16 v[140:143], v[76:79], v[48:51], v[40:43]
	v_mfma_f32_16x16x32_bf16 v[148:151], v[80:83], v[48:51], v[40:43]
	v_mfma_f32_16x16x32_bf16 v[156:159], v[84:87], v[48:51], v[40:43]
	ds_read_b64_tr_b16 v[40:41], v190
	ds_read_b64_tr_b16 v[42:43], v191
	ds_read_b64_tr_b16 v[44:45], v192
	ds_read_b64_tr_b16 v[46:47], v193
	ds_read_b64_tr_b16 v[160:161], v194
	ds_read_b64_tr_b16 v[162:163], v195
	ds_read_b64_tr_b16 v[210:211], v197
	ds_read_b64_tr_b16 v[212:213], v202
	ds_read_b64_tr_b16 v[214:215], v203
	ds_read_b64_tr_b16 v[216:217], v204
	ds_read_b64_tr_b16 v[230:231], v205
	ds_read_b64_tr_b16 v[232:233], v206
	ds_read_b64_tr_b16 v[234:235], v207
	ds_read_b64_tr_b16 v[236:237], v208
	s_nop 0
	s_waitcnt lgkmcnt(0)
	s_waitcnt lgkmcnt(0)
	s_waitcnt lgkmcnt(0)
	s_waitcnt lgkmcnt(0)
	s_nop 0
	v_mfma_f32_16x16x32_bf16 v[72:75], v[36:39], v[64:67], v[88:91]
	v_mfma_f32_16x16x32_bf16 v[48:51], v[36:39], v[92:95], v[52:55]
	v_mfma_f32_16x16x32_bf16 v[84:87], v[40:43], v[64:67], v[98:101]
	v_mfma_f32_16x16x32_bf16 v[40:43], v[40:43], v[92:95], v[56:59]
	v_mfma_f32_16x16x32_bf16 v[80:83], v[44:47], v[64:67], v[102:105]
	v_mfma_f32_16x16x32_bf16 v[36:39], v[44:47], v[92:95], v[60:63]
	v_mfma_f32_16x16x32_bf16 v[76:79], v[160:163], v[64:67], v[106:109]
	v_mfma_f32_16x16x32_bf16 v[44:47], v[160:163], v[92:95], v[68:71]
	v_mfma_f32_16x16x32_bf16 v[88:91], v[210:213], v[64:67], v[110:113]
	v_mfma_f32_16x16x32_bf16 v[52:55], v[210:213], v[92:95], v[118:121]
	v_mfma_f32_16x16x32_bf16 v[108:111], v[214:217], v[64:67], v[136:139]
	v_mfma_f32_16x16x32_bf16 v[56:59], v[214:217], v[92:95], v[140:143]
	v_mfma_f32_16x16x32_bf16 v[112:115], v[230:233], v[64:67], v[144:147]
	v_mfma_f32_16x16x32_bf16 v[60:63], v[230:233], v[92:95], v[148:151]
	v_mfma_f32_16x16x32_bf16 v[68:71], v[234:237], v[64:67], v[152:155]
	v_mfma_f32_16x16x32_bf16 v[64:67], v[234:237], v[92:95], v[156:159]
	s_andn2_b64 vcc, exec, s[6:7]
	s_cbranch_vccz .LBB0_368
	s_branch .LBB0_375

; #define LAS __attribute__((address_space(3)))
; __device__ __forceinline__ float shx(float v, int mask, int lane) { return __int_as_float(__builtin_amdgcn_ds_bpermute((lane ^ mask) << 2, __float_as_int(v))); }
; __device__ __forceinline__ void attn_phase(int wv, PP P, int L, LAS unsigned char* lds) {
;     ...
;                 for (int m = 0; m < 2; ++m) {
;                     f32x4 sa[4];
; #pragma unroll
;                     for (int nt = 0; nt < 4; ++nt) { sa[nt] = (f32x4){0.f, 0.f, 0.f, 0.f};
; #pragma unroll
;                         for (int kk = 0; kk < 2; ++kk) { const bf16x8 kf = *(const LAS bf16x8*)(lds + kbuf + (nt * 16 + fr) * 272 + (m * 64 + kk * 32 + fq * 8) * 2);
;                             sa[nt] = __builtin_amdgcn_mfma_f32_16x16x32_bf16(kf, qf[m][kk], sa[nt], 0, 0, 0); } }
;                     float mx = -INFINITY;
; #pragma unroll
;                     for (int nt = 0; nt < 4; ++nt)
; #pragma unroll
;                         for (int q = 0; q < 4; ++q) { const bool kv = (kt > 0) || (nt * 16 + fq * 4 + q >= 48); sa[nt][q] = kv ? sa[nt][q] * 0.125f : -INFINITY; mx = fmaxf(mx, sa[nt][q]); }
;                     mx = fmaxf(mx, shx(mx, 16, lane)); mx = fmaxf(mx, shx(mx, 32, lane));
;                     const float mnew = fmaxf(mrun[m], mx); const float alpha = __expf(mrun[m] - mnew); mrun[m] = mnew;
;                     float rsum = 0.f;
; #pragma unroll
;                     for (int nt = 0; nt < 4; ++nt)
; #pragma unroll
;                         for (int q = 0; q < 4; ++q) { sa[nt][q] = __expf(sa[nt][q] - mnew); rsum += sa[nt][q]; }
;                     rsum += shx(rsum, 16, lane); rsum += shx(rsum, 32, lane);
.LBB0_373:
	v_add_u32_e32 v122, s7, v171
	ds_read_b128 v[92:95], v122
	ds_read_b128 v[98:101], v122 offset:64
	s_waitcnt lgkmcnt(1)
	v_mfma_f32_16x16x32_bf16 v[92:95], v[92:95], v[12:15], 0
	ds_read_b128 v[102:105], v122 offset:4416
	ds_read_b128 v[118:121], v122 offset:8768
	ds_read_b128 v[136:139], v122 offset:13120
	s_waitcnt lgkmcnt(3)
	v_mfma_f32_16x16x32_bf16 v[92:95], v[98:101], v[4:7], v[92:95]
	ds_read_b128 v[98:101], v122 offset:4352
	ds_read_b128 v[210:213], v122 offset:4544
	ds_read_b128 v[214:217], v122 offset:8896
	s_waitcnt lgkmcnt(2)
	v_mfma_f32_16x16x32_bf16 v[98:101], v[98:101], v[12:15], 0
	s_nop 2
	v_mul_f32_e32 v97, 0x3e000000, v92
	v_mul_f32_e32 v106, 0x3e000000, v93
	v_max3_f32 v97, v97, s52, v106
	v_mfma_f32_16x16x32_bf16 v[98:101], v[102:105], v[4:7], v[98:101]
	ds_read_b128 v[102:105], v122 offset:8704
	v_mul_f32_e32 v106, 0x3e000000, v94
	v_mul_f32_e32 v107, 0x3e000000, v95
	s_waitcnt lgkmcnt(0)
	v_mfma_f32_16x16x32_bf16 v[102:105], v[102:105], v[12:15], 0
	v_max3_f32 v97, v97, v106, v107
	s_nop 1
	v_mul_f32_e32 v106, 0x3e000000, v98
	v_mul_f32_e32 v107, 0x3e000000, v99
	v_mfma_f32_16x16x32_bf16 v[102:105], v[118:121], v[4:7], v[102:105]
	ds_read_b128 v[118:121], v122 offset:13056
	v_max3_f32 v97, v97, v106, v107
	v_mul_f32_e32 v106, 0x3e000000, v100
	s_waitcnt lgkmcnt(0)
	v_mfma_f32_16x16x32_bf16 v[118:121], v[118:121], v[12:15], 0
	v_mul_f32_e32 v107, 0x3e000000, v101
	v_max3_f32 v97, v97, v106, v107
	s_nop 0
	v_mul_f32_e32 v106, 0x3e000000, v102
	v_mfma_f32_16x16x32_bf16 v[160:163], v[136:139], v[4:7], v[118:121]
	v_mul_f32_e32 v107, 0x3e000000, v103
	v_max3_f32 v97, v97, v106, v107
	v_mul_f32_e32 v106, 0x3e000000, v104
	v_mul_f32_e32 v107, 0x3e000000, v105
	v_max3_f32 v97, v97, v106, v107
	s_nop 2
	v_mul_f32_e32 v106, 0x3e000000, v160
	v_mul_f32_e32 v107, 0x3e000000, v161
	v_max3_f32 v97, v97, v106, v107
	v_mul_f32_e32 v106, 0x3e000000, v162
	v_mul_f32_e32 v107, 0x3e000000, v163
	v_max3_f32 v97, v97, v106, v107
	v_mov_b32_e32 v106, v97
	s_nop 1
	v_permlane16_swap_b32_e32 v97, v106
	ds_read_b128 v[230:233], v122 offset:13248
	s_waitcnt lgkmcnt(1)
	v_max_f32_e32 v106, v106, v106
	v_max_f32_e32 v97, v97, v106
	v_mov_b32_e32 v106, v97
	s_nop 1
	v_permlane32_swap_b32_e32 v97, v106
	s_waitcnt lgkmcnt(0)
	v_max3_f32 v131, v96, v97, v106
	v_fma_f32 v92, v92, s50, -v131
	v_mul_f32_e32 v92, 0x3fb8aa3b, v92
	v_exp_f32_e32 v121, v92
	v_fma_f32 v92, v93, s50, -v131
	v_mul_f32_e32 v92, 0x3fb8aa3b, v92
	v_exp_f32_e32 v123, v92
	v_fma_f32 v92, v94, s50, -v131
	v_mul_f32_e32 v92, 0x3fb8aa3b, v92
	v_exp_f32_e32 v137, v92
	v_fma_f32 v92, v95, s50, -v131
	v_mul_f32_e32 v92, 0x3fb8aa3b, v92
	v_exp_f32_e32 v139, v92
	v_fma_f32 v92, v98, s50, -v131
	v_mul_f32_e32 v92, 0x3fb8aa3b, v92
	v_exp_f32_e32 v141, v92
	v_fma_f32 v92, v99, s50, -v131
	v_mul_f32_e32 v92, 0x3fb8aa3b, v92
	v_sub_f32_e32 v96, v96, v131
	v_exp_f32_e32 v143, v92
	v_fma_f32 v92, v100, s50, -v131
	v_mul_f32_e32 v96, 0x3fb8aa3b, v96
	v_mul_f32_e32 v92, 0x3fb8aa3b, v92
	v_exp_f32_e32 v145, v92
	v_fma_f32 v92, v101, s50, -v131
	v_exp_f32_e32 v116, v96
	v_mul_f32_e32 v92, 0x3fb8aa3b, v92
	v_exp_f32_e32 v147, v92
	v_fma_f32 v92, v102, s50, -v131
	v_mul_f32_e32 v92, 0x3fb8aa3b, v92
	v_exp_f32_e32 v149, v92
	v_fma_f32 v92, v103, s50, -v131
	v_pk_mul_f32 v[102:103], v[86:87], v[116:117] op_sel_hi:[1,0]
	v_pk_mul_f32 v[100:101], v[84:85], v[116:117] op_sel_hi:[1,0]
	v_pk_mul_f32 v[86:87], v[110:111], v[116:117] op_sel_hi:[1,0]
	v_pk_mul_f32 v[84:85], v[108:109], v[116:117] op_sel_hi:[1,0]
	ds_read_b128 v[108:111], v122 offset:128
	v_pk_mul_f32 v[98:99], v[82:83], v[116:117] op_sel_hi:[1,0]
	v_pk_mul_f32 v[96:97], v[80:81], v[116:117] op_sel_hi:[1,0]
	v_pk_mul_f32 v[82:83], v[114:115], v[116:117] op_sel_hi:[1,0]
	v_pk_mul_f32 v[80:81], v[112:113], v[116:117] op_sel_hi:[1,0]
	ds_read_b128 v[112:115], v122 offset:192
	s_waitcnt lgkmcnt(1)
	v_mfma_f32_16x16x32_bf16 v[108:111], v[108:111], v[8:11], 0
	v_mul_f32_e32 v92, 0x3fb8aa3b, v92
	v_exp_f32_e32 v151, v92
	v_fma_f32 v92, v104, s50, -v131
	s_waitcnt lgkmcnt(0)
	v_mfma_f32_16x16x32_bf16 v[108:111], v[112:115], v[16:19], v[108:111]
	ds_read_b128 v[112:115], v122 offset:4480
	v_mul_f32_e32 v92, 0x3fb8aa3b, v92
	v_exp_f32_e32 v153, v92
	s_waitcnt lgkmcnt(0)
	v_mfma_f32_16x16x32_bf16 v[112:115], v[112:115], v[8:11], 0
	s_nop 2
	v_mul_f32_e32 v118, 0x3e000000, v108
	v_mul_f32_e32 v119, 0x3e000000, v109
	v_max3_f32 v118, v118, s52, v119
	v_mfma_f32_16x16x32_bf16 v[112:115], v[210:213], v[16:19], v[112:115]
	ds_read_b128 v[210:213], v122 offset:8832
	v_mul_f32_e32 v119, 0x3e000000, v110
	v_mul_f32_e32 v120, 0x3e000000, v111
	s_waitcnt lgkmcnt(0)
	v_mfma_f32_16x16x32_bf16 v[210:213], v[210:213], v[8:11], 0
	v_max3_f32 v118, v118, v119, v120
	s_nop 1
	v_mul_f32_e32 v119, 0x3e000000, v112
	v_mul_f32_e32 v120, 0x3e000000, v113
	v_mfma_f32_16x16x32_bf16 v[210:213], v[214:217], v[16:19], v[210:213]
	ds_read_b128 v[214:217], v122 offset:13184
	v_max3_f32 v118, v118, v119, v120
	v_mul_f32_e32 v119, 0x3e000000, v114
	s_waitcnt lgkmcnt(0)
	v_mfma_f32_16x16x32_bf16 v[214:217], v[214:217], v[8:11], 0
	v_mul_f32_e32 v120, 0x3e000000, v115
	v_max3_f32 v118, v118, v119, v120
	s_nop 0
	v_mul_f32_e32 v119, 0x3e000000, v210
	v_mfma_f32_16x16x32_bf16 v[214:217], v[230:233], v[16:19], v[214:217]
	v_mul_f32_e32 v120, 0x3e000000, v211
	v_max3_f32 v118, v118, v119, v120
	v_mul_f32_e32 v119, 0x3e000000, v212
	v_mul_f32_e32 v120, 0x3e000000, v213
	v_max3_f32 v118, v118, v119, v120
	s_nop 2
	v_mul_f32_e32 v119, 0x3e000000, v214
	v_mul_f32_e32 v120, 0x3e000000, v215
	v_max3_f32 v118, v118, v119, v120
	v_mul_f32_e32 v119, 0x3e000000, v216
	v_mul_f32_e32 v120, 0x3e000000, v217
	v_max3_f32 v118, v118, v119, v120
	v_mov_b32_e32 v119, v118
	s_nop 1
	v_permlane16_swap_b32_e32 v118, v119
	v_fma_f32 v92, v105, s50, -v131
	v_mul_f32_e32 v92, 0x3fb8aa3b, v92
	v_exp_f32_e32 v155, v92
	v_fma_f32 v92, v160, s50, -v131
	s_waitcnt lgkmcnt(0)
; __device__ __forceinline__ float shx(float v, int mask, int lane) { return __int_as_float(__builtin_amdgcn_ds_bpermute((lane ^ mask) << 2, __float_as_int(v))); }
; __device__ __forceinline__ void attn_phase(int wv, PP P, int L, LAS unsigned char* lds) {
;     ...
;                     float mx = -INFINITY;
; #pragma unroll
;                     for (int nt = 0; nt < 4; ++nt)
; #pragma unroll
;                         for (int q = 0; q < 4; ++q) { const bool kv = (kt > 0) || (nt * 16 + fq * 4 + q >= 48); sa[nt][q] = kv ? sa[nt][q] * 0.125f : -INFINITY; mx = fmaxf(mx, sa[nt][q]); }
;                     mx = fmaxf(mx, shx(mx, 16, lane)); mx = fmaxf(mx, shx(mx, 32, lane));
;                     const float mnew = fmaxf(mrun[m], mx); const float alpha = __expf(mrun[m] - mnew); mrun[m] = mnew;
;                     float rsum = 0.f;
; #pragma unroll
;                     for (int nt = 0; nt < 4; ++nt)
; #pragma unroll
;                         for (int q = 0; q < 4; ++q) { sa[nt][q] = __expf(sa[nt][q] - mnew); rsum += sa[nt][q]; }
;                     rsum += shx(rsum, 16, lane); rsum += shx(rsum, 32, lane);
;                     lrun[m] = lrun[m] * alpha + rsum;
; #pragma unroll
;                     for (int e = 0; e < 8; ++e) O[m][e] *= alpha;
	v_max_f32_e32 v119, v119, v119
	v_max_f32_e32 v118, v118, v119
	v_mov_b32_e32 v119, v118
	s_nop 1
	v_permlane32_swap_b32_e32 v118, v119
	v_mul_f32_e32 v92, 0x3fb8aa3b, v92
	v_exp_f32_e32 v157, v92
	v_fma_f32 v92, v161, s50, -v131
	v_mul_f32_e32 v92, 0x3fb8aa3b, v92
	s_waitcnt lgkmcnt(0)
	v_max3_f32 v209, v117, v118, v119
	v_fma_f32 v108, v108, s50, -v209
	v_mul_f32_e32 v108, 0x3fb8aa3b, v108
	v_exp_f32_e32 v120, v108
	v_fma_f32 v108, v109, s50, -v209
	v_mul_f32_e32 v108, 0x3fb8aa3b, v108
	v_exp_f32_e32 v122, v108
	v_fma_f32 v108, v110, s50, -v209
	v_mul_f32_e32 v108, 0x3fb8aa3b, v108
	v_exp_f32_e32 v136, v108
	v_fma_f32 v108, v111, s50, -v209
	v_mul_f32_e32 v108, 0x3fb8aa3b, v108
	v_exp_f32_e32 v138, v108
	v_fma_f32 v108, v112, s50, -v209
	v_mul_f32_e32 v108, 0x3fb8aa3b, v108
	v_exp_f32_e32 v140, v108
	v_fma_f32 v108, v113, s50, -v209
	v_mul_f32_e32 v108, 0x3fb8aa3b, v108
	v_exp_f32_e32 v142, v108
	v_fma_f32 v108, v114, s50, -v209
	v_mul_f32_e32 v108, 0x3fb8aa3b, v108
	v_exp_f32_e32 v144, v108
	v_fma_f32 v108, v115, s50, -v209
	v_mul_f32_e32 v108, 0x3fb8aa3b, v108
	v_fma_f32 v110, v211, s50, -v209
	v_exp_f32_e32 v146, v108
	v_fma_f32 v108, v210, s50, -v209
	v_mul_f32_e32 v110, 0x3fb8aa3b, v110
	v_mul_f32_e32 v108, 0x3fb8aa3b, v108
	v_exp_f32_e32 v150, v110
	v_fma_f32 v110, v212, s50, -v209
	v_exp_f32_e32 v148, v108
	v_pk_add_f32 v[108:109], v[120:121], 0 op_sel_hi:[1,0]
	v_mul_f32_e32 v110, 0x3fb8aa3b, v110
	v_pk_add_f32 v[108:109], v[122:123], v[108:109]
	v_exp_f32_e32 v152, v110
	v_fma_f32 v110, v213, s50, -v209
	v_pk_add_f32 v[108:109], v[136:137], v[108:109]
	v_mul_f32_e32 v110, 0x3fb8aa3b, v110
	v_pk_add_f32 v[108:109], v[138:139], v[108:109]
	v_exp_f32_e32 v154, v110
	v_fma_f32 v110, v214, s50, -v209
	v_pk_add_f32 v[108:109], v[140:141], v[108:109]
	v_mul_f32_e32 v110, 0x3fb8aa3b, v110
	v_pk_add_f32 v[108:109], v[142:143], v[108:109]
	v_exp_f32_e32 v156, v110
	v_fma_f32 v110, v215, s50, -v209
	v_pk_add_f32 v[108:109], v[144:145], v[108:109]
	v_mul_f32_e32 v110, 0x3fb8aa3b, v110
	v_exp_f32_e32 v159, v92
	v_fma_f32 v92, v162, s50, -v131
	v_pk_add_f32 v[108:109], v[146:147], v[108:109]
	v_exp_f32_e32 v158, v110
	v_fma_f32 v110, v216, s50, -v209
	v_mul_f32_e32 v92, 0x3fb8aa3b, v92
	v_pk_add_f32 v[108:109], v[148:149], v[108:109]
	v_mul_f32_e32 v110, 0x3fb8aa3b, v110
	v_exp_f32_e32 v161, v92
	v_fma_f32 v92, v163, s50, -v131
	v_exp_f32_e32 v160, v110
	v_fma_f32 v110, v217, s50, -v209
	v_pk_add_f32 v[108:109], v[150:151], v[108:109]
	v_mul_f32_e32 v92, 0x3fb8aa3b, v92
	v_mul_f32_e32 v110, 0x3fb8aa3b, v110
	v_pk_add_f32 v[108:109], v[152:153], v[108:109]
	v_exp_f32_e32 v163, v92
	v_exp_f32_e32 v162, v110
	v_pk_add_f32 v[108:109], v[154:155], v[108:109]
	v_pk_mul_f32 v[106:107], v[74:75], v[116:117] op_sel_hi:[1,0]
	v_pk_add_f32 v[108:109], v[156:157], v[108:109]
	v_pk_mul_f32 v[104:105], v[72:73], v[116:117] op_sel_hi:[1,0]
	v_pk_add_f32 v[108:109], v[158:159], v[108:109]
	v_pk_mul_f32 v[94:95], v[78:79], v[116:117] op_sel_hi:[1,0]
	v_pk_add_f32 v[108:109], v[160:161], v[108:109]
	v_pk_mul_f32 v[92:93], v[76:77], v[116:117] op_sel_hi:[1,0]
	v_pk_add_f32 v[108:109], v[162:163], v[108:109]
	v_mov_b32_e32 v111, v109
	v_mov_b32_e32 v110, v108
	s_nop 0
	v_permlane16_swap_b32_e32 v109, v111
	v_permlane16_swap_b32_e32 v108, v110
	v_pk_mul_f32 v[90:91], v[90:91], v[116:117] op_sel_hi:[1,0]
	v_pk_mul_f32 v[88:89], v[88:89], v[116:117] op_sel_hi:[1,0]
	v_pk_mul_f32 v[74:75], v[70:71], v[116:117] op_sel_hi:[1,0]
	v_pk_mul_f32 v[72:73], v[68:69], v[116:117] op_sel_hi:[1,0]
	s_waitcnt lgkmcnt(0)
	v_pk_add_f32 v[108:109], v[108:109], v[110:111]
	v_sub_f32_e32 v117, v117, v209
	v_mov_b32_e32 v111, v109
	v_mov_b32_e32 v110, v108
	s_nop 0
	v_permlane32_swap_b32_e32 v109, v111
	v_permlane32_swap_b32_e32 v108, v110
	v_mul_f32_e32 v117, 0x3fb8aa3b, v117
	v_exp_f32_e32 v214, v117
	v_mov_b32_e32 v215, v116
	v_add_u32_e32 v216, s7, v167
	s_waitcnt lgkmcnt(0)
; __device__ __forceinline__ u32x2 trr(unsigned addr) { u32x2 r; asm volatile("ds_read_b64_tr_b16 %0, %1" : "=&v"(r) : "v"(addr) : "memory"); return r; }
; __device__ __forceinline__ void trw4(u32x2& a, u32x2& b, u32x2& c, u32x2& d) { asm volatile("s_waitcnt lgkmcnt(0)" : "+v"(a), "+v"(b), "+v"(c), "+v"(d) : : "memory"); }
; __device__ __forceinline__ unsigned pack2(float lo, float hi) { unsigned r; asm("v_cvt_pk_bf16_f32 %0, %1, %2" : "=v"(r) : "v"(lo), "v"(hi)); return r; }
; __device__ __forceinline__ void attn_phase(int wv, PP P, int L, LAS unsigned char* lds) {
;     ...
; #pragma unroll
;                     for (int e = 0; e < 8; ++e) O[m][e] *= alpha;
; #pragma unroll
;                     for (int kp = 0; kp < 2; ++kp) { u32x4 t; t.x = pack2(sa[2 * kp][0], sa[2 * kp][1]); t.y = pack2(sa[2 * kp][2], sa[2 * kp][3]); t.z = pack2(sa[2 * kp + 1][0], sa[2 * kp + 1][1]); t.w = pack2(sa[2 * kp + 1][2], sa[2 * kp + 1][3]);
;                         pf[m][kp] = __builtin_bit_cast(bf16x8, t); }
;                 }
;                 const unsigned trv = ldsb + vbuf + (4 * fq + trq) * 272 + (4 * trp) * 2;
; #pragma unroll
;                 for (int kp = 0; kp < 2; ++kp) {
;                     u32x2 vl[8], vh[8];
; #pragma unroll
;                     for (int e = 0; e < 8; ++e) { vl[e] = trr(trv + (32 * kp) * 272 + e * 32); vh[e] = trr(trv + (32 * kp + 16) * 272 + e * 32); }
;                     trw4(vl[0], vl[1], vl[2], vl[3]); trw4(vl[4], vl[5], vl[6], vl[7]); trw4(vh[0], vh[1], vh[2], vh[3]); trw4(vh[4], vh[5], vh[6], vh[7]);
; #pragma unroll
;                     for (int e = 0; e < 8; ++e) { const bf16x8 vf = mk8(vl[e], vh[e]);
;                         O[0][e] = __builtin_amdgcn_mfma_f32_16x16x32_bf16(vf, pf[0][kp], O[0][e], 0, 0, 0);
;                         O[1][e] = __builtin_amdgcn_mfma_f32_16x16x32_bf16(vf, pf[1][kp], O[1][e], 0, 0, 0); }
;                 }
	v_pk_add_f32 v[108:109], v[108:109], v[110:111]
	v_pk_mul_f32 v[116:117], v[40:41], v[214:215] op_sel_hi:[1,0]
	v_pk_fma_f32 v[134:135], v[134:135], v[214:215], v[108:109]
	v_pk_mul_f32 v[108:109], v[44:45], v[214:215] op_sel_hi:[1,0]
	v_pk_mul_f32 v[44:45], v[56:57], v[214:215] op_sel_hi:[1,0]
	v_pk_mul_f32 v[40:41], v[60:61], v[214:215] op_sel_hi:[1,0]
	v_add_u32_e32 v56, 0x8800, v216
	ds_read_b64_tr_b16 v[60:61], v56
	v_pk_mul_f32 v[118:119], v[42:43], v[214:215] op_sel_hi:[1,0]
	v_pk_mul_f32 v[42:43], v[62:63], v[214:215] op_sel_hi:[1,0]
	v_add_u32_e32 v57, 0x9900, v216
	ds_read_b64_tr_b16 v[62:63], v57
	v_cvt_pk_bf16_f32 v77, v137, v139
	v_pk_mul_f32 v[210:211], v[48:49], v[214:215] op_sel_hi:[1,0]
	v_pk_mul_f32 v[48:49], v[52:53], v[214:215] op_sel_hi:[1,0]
	v_cvt_pk_bf16_f32 v53, v136, v138
	v_add_u32_e32 v56, 0x8820, v216
	ds_read_b64_tr_b16 v[136:137], v56
	v_add_u32_e32 v56, 0x9920, v216
	ds_read_b64_tr_b16 v[138:139], v56
	v_cvt_pk_bf16_f32 v78, v141, v143
	v_pk_mul_f32 v[212:213], v[50:51], v[214:215] op_sel_hi:[1,0]
	v_pk_mul_f32 v[50:51], v[54:55], v[214:215] op_sel_hi:[1,0]
	v_cvt_pk_bf16_f32 v54, v140, v142
	v_add_u32_e32 v56, 0x8840, v216
	ds_read_b64_tr_b16 v[140:141], v56
	v_add_u32_e32 v56, 0x9940, v216
	ds_read_b64_tr_b16 v[142:143], v56
	v_cvt_pk_bf16_f32 v79, v145, v147
	v_cvt_pk_bf16_f32 v55, v144, v146
	v_add_u32_e32 v56, 0x8860, v216
	ds_read_b64_tr_b16 v[144:145], v56
	v_add_u32_e32 v56, 0x9960, v216
	ds_read_b64_tr_b16 v[146:147], v56
	v_cvt_pk_bf16_f32 v68, v149, v151
	v_pk_mul_f32 v[112:113], v[36:37], v[214:215] op_sel_hi:[1,0]
	v_pk_mul_f32 v[36:37], v[64:65], v[214:215] op_sel_hi:[1,0]
	v_cvt_pk_bf16_f32 v64, v148, v150
	v_add_u32_e32 v56, 0x8880, v216
	ds_read_b64_tr_b16 v[148:149], v56
	v_add_u32_e32 v56, 0x9980, v216
	ds_read_b64_tr_b16 v[150:151], v56
	v_cvt_pk_bf16_f32 v69, v153, v155
	v_cvt_pk_bf16_f32 v65, v152, v154
	v_add_u32_e32 v56, 0x88a0, v216
	ds_read_b64_tr_b16 v[152:153], v56
	v_add_u32_e32 v56, 0x99a0, v216
	ds_read_b64_tr_b16 v[154:155], v56
	v_cvt_pk_bf16_f32 v70, v157, v159
	v_pk_mul_f32 v[114:115], v[38:39], v[214:215] op_sel_hi:[1,0]
	v_pk_mul_f32 v[38:39], v[66:67], v[214:215] op_sel_hi:[1,0]
	v_cvt_pk_bf16_f32 v66, v156, v158
	v_add_u32_e32 v56, 0x88c0, v216
	ds_read_b64_tr_b16 v[156:157], v56
	v_add_u32_e32 v56, 0x99c0, v216
	ds_read_b64_tr_b16 v[158:159], v56
	v_cvt_pk_bf16_f32 v76, v121, v123
	v_cvt_pk_bf16_f32 v52, v120, v122
	v_add_u32_e32 v56, 0x88e0, v216
	ds_read_b64_tr_b16 v[120:121], v56
	v_add_u32_e32 v56, 0x99e0, v216
	ds_read_b64_tr_b16 v[122:123], v56
	s_waitcnt lgkmcnt(0)
	s_waitcnt lgkmcnt(0)
	s_waitcnt lgkmcnt(0)
	v_pk_mul_f32 v[110:111], v[46:47], v[214:215] op_sel_hi:[1,0]
	v_pk_mul_f32 v[46:47], v[58:59], v[214:215] op_sel_hi:[1,0]
	s_waitcnt lgkmcnt(0)
	v_mfma_f32_16x16x32_bf16 v[56:59], v[60:63], v[76:79], v[104:107]
	v_cvt_pk_bf16_f32 v71, v161, v163
	v_cvt_pk_bf16_f32 v67, v160, v162
	v_mfma_f32_16x16x32_bf16 v[100:103], v[136:139], v[76:79], v[100:103]
	v_mfma_f32_16x16x32_bf16 v[104:107], v[136:139], v[52:55], v[116:119]
	v_mfma_f32_16x16x32_bf16 v[96:99], v[140:143], v[76:79], v[96:99]
	v_mfma_f32_16x16x32_bf16 v[112:115], v[140:143], v[52:55], v[112:115]
	v_mfma_f32_16x16x32_bf16 v[136:139], v[152:155], v[76:79], v[84:87]
	v_mfma_f32_16x16x32_bf16 v[140:143], v[152:155], v[52:55], v[44:47]
	v_mfma_f32_16x16x32_bf16 v[152:155], v[120:123], v[76:79], v[72:75]
	s_nop 1
	v_add_u32_e32 v44, 0xbb20, v216
	v_add_u32_e32 v46, 0xaa40, v216
	v_mfma_f32_16x16x32_bf16 v[120:123], v[120:123], v[52:55], v[36:39]
	s_nop 2
	v_add_u32_e32 v38, 0xaa00, v216
	ds_read_b64_tr_b16 v[36:37], v38
	v_mfma_f32_16x16x32_bf16 v[88:91], v[148:151], v[76:79], v[88:91]
	v_mfma_f32_16x16x32_bf16 v[116:119], v[148:151], v[52:55], v[48:51]
	v_mfma_f32_16x16x32_bf16 v[148:151], v[156:159], v[52:55], v[40:43]
	s_nop 1
	v_add_u32_e32 v48, 0xbb40, v216
	v_add_u32_e32 v40, 0xbb00, v216
	ds_read_b64_tr_b16 v[38:39], v40
	v_add_u32_e32 v42, 0xaa20, v216
	ds_read_b64_tr_b16 v[40:41], v42
	ds_read_b64_tr_b16 v[42:43], v44
	ds_read_b64_tr_b16 v[44:45], v46
	ds_read_b64_tr_b16 v[46:47], v48
	v_mfma_f32_16x16x32_bf16 v[60:63], v[60:63], v[52:55], v[210:213]
	v_add_u32_e32 v48, 0xaa60, v216
	v_mfma_f32_16x16x32_bf16 v[108:111], v[144:147], v[52:55], v[108:111]
	ds_read_b64_tr_b16 v[52:53], v48
	v_add_u32_e32 v48, 0xbb60, v216
	ds_read_b64_tr_b16 v[54:55], v48
	v_mfma_f32_16x16x32_bf16 v[92:95], v[144:147], v[76:79], v[92:95]
	v_add_u32_e32 v48, 0xaa80, v216
	v_mfma_f32_16x16x32_bf16 v[144:147], v[156:159], v[76:79], v[80:83]
	ds_read_b64_tr_b16 v[156:157], v48
	v_add_u32_e32 v48, 0xbb80, v216
	ds_read_b64_tr_b16 v[158:159], v48
	v_add_u32_e32 v48, 0xaaa0, v216
	ds_read_b64_tr_b16 v[160:161], v48
	v_add_u32_e32 v48, 0xbba0, v216
	ds_read_b64_tr_b16 v[162:163], v48
	v_add_u32_e32 v48, 0xaac0, v216
	ds_read_b64_tr_b16 v[210:211], v48
	v_add_u32_e32 v48, 0xbbc0, v216
	ds_read_b64_tr_b16 v[212:213], v48
	v_add_u32_e32 v48, 0xaae0, v216
	ds_read_b64_tr_b16 v[214:215], v48
	v_add_u32_e32 v48, 0xbbe0, v216
	ds_read_b64_tr_b16 v[216:217], v48
	s_waitcnt lgkmcnt(0)
	s_waitcnt lgkmcnt(0)
	s_waitcnt lgkmcnt(0)
	s_nop 0
	s_waitcnt lgkmcnt(0)
	v_mfma_f32_16x16x32_bf16 v[72:75], v[36:39], v[68:71], v[56:59]
	v_mfma_f32_16x16x32_bf16 v[48:51], v[36:39], v[64:67], v[60:63]
	v_mfma_f32_16x16x32_bf16 v[84:87], v[40:43], v[68:71], v[100:103]
	v_mfma_f32_16x16x32_bf16 v[40:43], v[40:43], v[64:67], v[104:107]
	v_mfma_f32_16x16x32_bf16 v[80:83], v[44:47], v[68:71], v[96:99]
	v_mfma_f32_16x16x32_bf16 v[36:39], v[44:47], v[64:67], v[112:115]
	s_nop 1
	v_mov_b32_e32 v96, v131
	v_mfma_f32_16x16x32_bf16 v[76:79], v[52:55], v[68:71], v[92:95]
	v_mfma_f32_16x16x32_bf16 v[44:47], v[52:55], v[64:67], v[108:111]
	v_mfma_f32_16x16x32_bf16 v[88:91], v[156:159], v[68:71], v[88:91]
	v_mfma_f32_16x16x32_bf16 v[52:55], v[156:159], v[64:67], v[116:119]
	v_mfma_f32_16x16x32_bf16 v[108:111], v[160:163], v[68:71], v[136:139]
	s_nop 1
	v_mov_b32_e32 v117, v209
	v_mfma_f32_16x16x32_bf16 v[56:59], v[160:163], v[64:67], v[140:143]
	v_mfma_f32_16x16x32_bf16 v[112:115], v[210:213], v[68:71], v[144:147]
	v_mfma_f32_16x16x32_bf16 v[60:63], v[210:213], v[64:67], v[148:151]
	v_mfma_f32_16x16x32_bf16 v[68:71], v[214:217], v[68:71], v[152:155]
	v_mfma_f32_16x16x32_bf16 v[64:67], v[214:217], v[64:67], v[120:123]
	s_cmp_eq_u32 s24, s6
	s_cbranch_scc1 .LBB0_375

; __device__ __forceinline__ float shx(float v, int mask, int lane) { return __int_as_float(__builtin_amdgcn_ds_bpermute((lane ^ mask) << 2, __float_as_int(v))); }
; __device__ __forceinline__ unsigned pack2(float lo, float hi) { unsigned r; asm("v_cvt_pk_bf16_f32 %0, %1, %2" : "=v"(r) : "v"(lo), "v"(hi)); return r; }
; __device__ __forceinline__ void attn_phase(int wv, PP P, int L, LAS unsigned char* lds) {
;     ...
;         const float* dn = P->da_norm + (size_t)L * 128;
;         const float i0 = __builtin_amdgcn_rcpf(lrun[0]), i1 = lam * __builtin_amdgcn_rcpf(lrun[1]); float ss = 0.f;
; #pragma unroll
;         for (int e = 0; e < 8; ++e) { O[0][e] = O[0][e] * i0 - O[1][e] * i1; ss += O[0][e][0] * O[0][e][0] + O[0][e][1] * O[0][e][1] + O[0][e][2] * O[0][e][2] + O[0][e][3] * O[0][e][3]; }
;         ss += shx(ss, 16, lane); ss += shx(ss, 32, lane);
;         const int pos = q0 + w * 16 + fr; const float r = (pos < PADN) ? 0.f : rsqrtf(ss * (1.0f / 128.0f) + EPS) * (1.0f - lam_init);
; #pragma unroll
;         for (int e = 0; e < 8; ++e) { const f32x4 g4 = *(const f32x4*)(dn + e * 16 + fq * 4); u32x2 o; o.x = pack2(O[0][e][0] * r * g4[0], O[0][e][1] * r * g4[1]); o.y = pack2(O[0][e][2] * r * g4[2], O[0][e][3] * r * g4[3]);
;             if (pos < PADN) { o.x = 0u; o.y = 0u; }
;             if (wact) *(u32x2*)(cat + ((size_t)b * LP + pos) * D + 1536 + h * 128 + e * 16 + fq * 4) = o; }
.LBB0_375:
	s_waitcnt vmcnt(3)
	v_rcp_f32_e32 v4, v134
	v_rcp_f32_e32 v2, v135
	s_load_dwordx2 s[24:25], s[10:11], 0x40
	v_cmp_gt_i32_e64 s[6:7], 48, v132
	v_mul_f32_e32 v4, v164, v4
	s_waitcnt vmcnt(2)
	v_pk_mul_f32 v[8:9], v[48:49], v[4:5] op_sel_hi:[1,0]
	v_pk_mul_f32 v[6:7], v[50:51], v[4:5] op_sel_hi:[1,0]
	v_pk_fma_f32 v[48:49], v[72:73], v[2:3], v[8:9] op_sel_hi:[1,0,1] neg_lo:[0,0,1] neg_hi:[0,0,1]
	s_waitcnt vmcnt(0)
	v_pk_fma_f32 v[34:35], v[74:75], v[2:3], v[6:7] op_sel_hi:[1,0,1] neg_lo:[0,0,1] neg_hi:[0,0,1]
	v_mul_f32_e32 v5, v49, v49
	v_fmac_f32_e32 v5, v48, v48
	v_fmac_f32_e32 v5, v34, v34
	v_fmac_f32_e32 v5, v35, v35
	v_pk_mul_f32 v[8:9], v[40:41], v[4:5] op_sel_hi:[1,0]
	v_pk_mul_f32 v[6:7], v[42:43], v[4:5] op_sel_hi:[1,0]
	v_pk_fma_f32 v[32:33], v[84:85], v[2:3], v[8:9] op_sel_hi:[1,0,1] neg_lo:[0,0,1] neg_hi:[0,0,1]
	v_pk_fma_f32 v[30:31], v[86:87], v[2:3], v[6:7] op_sel_hi:[1,0,1] neg_lo:[0,0,1] neg_hi:[0,0,1]
	v_mul_f32_e32 v6, v33, v33
	v_fmac_f32_e32 v6, v32, v32
	v_fmac_f32_e32 v6, v30, v30
	v_fmac_f32_e32 v6, v31, v31
	v_add_f32_e32 v5, v5, v6
	v_pk_mul_f32 v[8:9], v[36:37], v[4:5] op_sel_hi:[1,0]
	v_pk_mul_f32 v[6:7], v[38:39], v[4:5] op_sel_hi:[1,0]
	v_pk_fma_f32 v[28:29], v[80:81], v[2:3], v[8:9] op_sel_hi:[1,0,1] neg_lo:[0,0,1] neg_hi:[0,0,1]
	v_pk_fma_f32 v[26:27], v[82:83], v[2:3], v[6:7] op_sel_hi:[1,0,1] neg_lo:[0,0,1] neg_hi:[0,0,1]
	v_mul_f32_e32 v6, v29, v29
	v_fmac_f32_e32 v6, v28, v28
	v_fmac_f32_e32 v6, v26, v26
	v_fmac_f32_e32 v6, v27, v27
	v_add_f32_e32 v5, v6, v5
	v_pk_mul_f32 v[8:9], v[44:45], v[4:5] op_sel_hi:[1,0]
	v_pk_mul_f32 v[6:7], v[46:47], v[4:5] op_sel_hi:[1,0]
	v_pk_fma_f32 v[24:25], v[76:77], v[2:3], v[8:9] op_sel_hi:[1,0,1] neg_lo:[0,0,1] neg_hi:[0,0,1]
	v_pk_fma_f32 v[22:23], v[78:79], v[2:3], v[6:7] op_sel_hi:[1,0,1] neg_lo:[0,0,1] neg_hi:[0,0,1]
	v_mul_f32_e32 v6, v25, v25
	v_fmac_f32_e32 v6, v24, v24
	v_fmac_f32_e32 v6, v22, v22
	v_fmac_f32_e32 v6, v23, v23
	v_add_f32_e32 v5, v6, v5
	v_pk_mul_f32 v[8:9], v[52:53], v[4:5] op_sel_hi:[1,0]
	v_pk_mul_f32 v[6:7], v[54:55], v[4:5] op_sel_hi:[1,0]
	v_pk_fma_f32 v[20:21], v[88:89], v[2:3], v[8:9] op_sel_hi:[1,0,1] neg_lo:[0,0,1] neg_hi:[0,0,1]
	v_pk_fma_f32 v[18:19], v[90:91], v[2:3], v[6:7] op_sel_hi:[1,0,1] neg_lo:[0,0,1] neg_hi:[0,0,1]
	v_mul_f32_e32 v6, v21, v21
	v_fmac_f32_e32 v6, v20, v20
	v_fmac_f32_e32 v6, v18, v18
	v_fmac_f32_e32 v6, v19, v19
	v_add_f32_e32 v5, v6, v5
	v_pk_mul_f32 v[8:9], v[56:57], v[4:5] op_sel_hi:[1,0]
	v_pk_mul_f32 v[6:7], v[58:59], v[4:5] op_sel_hi:[1,0]
	v_pk_fma_f32 v[14:15], v[108:109], v[2:3], v[8:9] op_sel_hi:[1,0,1] neg_lo:[0,0,1] neg_hi:[0,0,1]
	v_pk_fma_f32 v[12:13], v[110:111], v[2:3], v[6:7] op_sel_hi:[1,0,1] neg_lo:[0,0,1] neg_hi:[0,0,1]
	v_mul_f32_e32 v6, v15, v15
	v_fmac_f32_e32 v6, v14, v14
	v_fmac_f32_e32 v6, v12, v12
	v_fmac_f32_e32 v6, v13, v13
	v_add_f32_e32 v5, v6, v5
	v_pk_mul_f32 v[10:11], v[60:61], v[4:5] op_sel_hi:[1,0]
	v_pk_mul_f32 v[6:7], v[62:63], v[4:5] op_sel_hi:[1,0]
	v_pk_fma_f32 v[10:11], v[112:113], v[2:3], v[10:11] op_sel_hi:[1,0,1] neg_lo:[0,0,1] neg_hi:[0,0,1]
	v_pk_fma_f32 v[8:9], v[114:115], v[2:3], v[6:7] op_sel_hi:[1,0,1] neg_lo:[0,0,1] neg_hi:[0,0,1]
	v_mul_f32_e32 v6, v11, v11
	v_fmac_f32_e32 v6, v10, v10
	v_fmac_f32_e32 v6, v8, v8
	v_fmac_f32_e32 v6, v9, v9
	v_add_f32_e32 v36, v6, v5
	v_pk_mul_f32 v[6:7], v[66:67], v[4:5] op_sel_hi:[1,0]
	v_pk_mul_f32 v[16:17], v[64:65], v[4:5] op_sel_hi:[1,0]
	v_pk_fma_f32 v[4:5], v[70:71], v[2:3], v[6:7] op_sel_hi:[1,0,1] neg_lo:[0,0,1] neg_hi:[0,0,1]
	v_pk_fma_f32 v[6:7], v[68:69], v[2:3], v[16:17] op_sel_hi:[1,0,1] neg_lo:[0,0,1] neg_hi:[0,0,1]
	v_cmp_lt_i32_e32 vcc, 47, v132
	v_mul_f32_e32 v2, v7, v7
	v_fmac_f32_e32 v2, v6, v6
	v_fmac_f32_e32 v2, v4, v4
	v_fmac_f32_e32 v2, v5, v5
	v_add_f32_e32 v2, v2, v36
	v_mov_b32_e32 v16, v2
	s_nop 1
	v_permlane16_swap_b32_e32 v2, v16
	v_mov_b32_e32 v38, 0
	s_waitcnt lgkmcnt(0)
	v_add_f32_e32 v2, v2, v16
	v_mov_b32_e32 v16, v2
	s_nop 1
	v_permlane32_swap_b32_e32 v2, v16
	s_and_saveexec_b64 s[26:27], vcc
	s_cbranch_execz .LBB0_377
	s_waitcnt lgkmcnt(0)
	v_add_f32_e32 v2, v2, v16
	v_fmamk_f32 v2, v2, 0x3c000000, v220
	v_mul_f32_e32 v16, 0x4b800000, v2
	v_cmp_gt_f32_e32 vcc, s96, v2
	s_nop 1
	v_cndmask_b32_e32 v2, v2, v16, vcc
	v_rsq_f32_e32 v2, v2
	s_nop 0
	v_mul_f32_e32 v16, 0x45800000, v2
	v_cndmask_b32_e32 v2, v2, v16, vcc
	v_mul_f32_e32 v38, v168, v2

;     __device__ bool next(int i, Unit& u) const {
;         const long L = (long)i * G + c; if (L >= nwg) return false;
;         int wgid = (int)L; { const int q = nwg / NXCD, r = nwg % NXCD, xcd = wgid % NXCD, off = wgid / NXCD; wgid = (xcd < r ? xcd * (q + 1) : r * (q + 1) + (xcd - r) * q) + off; }
;         const int nig = WGM * nN, gid = wgid / nig, fm = gid * WGM, gsz = (nM - fm) < WGM ? (nM - fm) : WGM;
;         u.pm = fm + ((wgid % nig) % gsz); u.pn = (wgid % nig) / gsz; return true;
;     }
; template <class Epi, int LDA, int LDB, int KK>
; __device__ __forceinline__ void gemm_phase(int wv, LAS unsigned char* lds, const Gemm g, const StaticOrder& S, const Epi& E) {
;     ...
;         const bool has_next = S.next(ui + 1, nxt);
.LBB0_761:
	s_mov_b32 s100, s101
	s_add_i32 s43, s44, 1
	s_mul_i32 s4, s43, s49
	s_mul_hi_u32 s5, s43, s48
	s_add_i32 s5, s5, s4
	s_mul_i32 s4, s43, s48
	s_add_u32 s18, s4, s30
	s_addc_u32 s19, s5, s34
	s_mov_b32 s101, 0
	s_cmp_lt_u32 s18, 0xb00
	s_cbranch_scc1 .Lup_h1
	s_sub_u32 s98, s18, 0xb00
	s_cmp_lt_u32 s98, 176
	s_cbranch_scc1 .Lup_h0
	s_movk_i32 s18, 0xb58
	s_branch .Lup_h1

; #define LAS __attribute__((address_space(3)))
; template <class Epi, int LDA, int LDB, int KK>
; __device__ __forceinline__ void gemm_phase(int wv, LAS unsigned char* lds, const Gemm g, const StaticOrder& S, const Epi& E) {
;     ...
;     for (;;) {
;         const bool has_next = S.next(ui + 1, nxt);
;         const char* nA = has_next ? (const char*)g.A + (size_t)nxt.pm * tstepA : cA; const char* nB = has_next ? (const char*)g.Bt + (size_t)nxt.pn * tstepB : cB;
;         if constexpr (Epi::ROWSCALE) { if (has_next && wid < 4) __builtin_amdgcn_global_load_lds((const unsigned*)(E.rsq + nxt.pm * 256 + wid * 64 + lane), (LAS unsigned*)(lds + 131072 + ((ui + 1) % 3) * 1024 + wid * 256), 4, 0, 0); }
;         for (int seg = 0, t = 0; seg < Epi::NSEG; ++seg) {
;           const int tend = Epi::HAS_MID ? (seg == 0 ? Epi::MID1 : (seg == 1 ? Epi::MID2 : nt)) : nt;
;           for (; t < tend; t += 2) {
.Lut_p_done:
	s_mov_b32 s24, s14
	s_mov_b32 s22, s16
	s_mov_b64 s[28:29], s[20:21]
	s_mov_b64 s[26:27], s[18:19]
	s_mov_b32 s44, s43
	s_mov_b32 s99, 0
	s_and_b64 vcc, exec, s[4:5]
	s_cbranch_vccz .LBB0_761
	s_branch .Lup_end
.Lut_owner:
	s_cmp_lg_u32 s95, 0
	s_cbranch_scc1 .Lut_o_wait
	s_sub_u32 s98, s81, 88
	s_cmp_lt_u32 s81, 88
	s_cselect_b32 s98, s81, s98
	s_add_u32 s99, s98, 32
	s_cmp_lt_u32 s98, 64
	s_cselect_b32 s98, s98, s99
	s_lshl_b32 s98, s98, 2
	s_add_u32 s98, s98, 0x201da800
	s_add_u32 s98, s10, s98
	s_addc_u32 s99, s11, 0
	s_add_u32 s100, s2, 1
	s_mov_b64 exec, 1
	v_mov_b32_e32 v148, 0
.Lut_poll:
	s_sleep 2
	global_load_dword v149, v148, s[98:99] sc1
	s_waitcnt vmcnt(0)
	v_cmp_gt_u32_e32 vcc, s100, v149
	s_cbranch_vccnz .Lut_poll
	buffer_inv sc1
	s_waitcnt vmcnt(0)
	s_mov_b64 exec, -1

; #define LAS __attribute__((address_space(3)))
; __device__ __forceinline__ int opaque_tid(int wv) { asm volatile("" : "+s"(wv)); unsigned z = 0u; asm volatile("" : "+v"(z)); const int l = __builtin_amdgcn_mbcnt_hi(~0u, __builtin_amdgcn_mbcnt_lo(~0u, z)); return (wv << 6) | l; }
; __device__ __forceinline__ void convert_weight(int wv, const float* __restrict__ src, int ldsrc, int Ksrc, bf16_t* dst, int ldd, int koff, int ntn, const float* kscale, int mode, LAS float* tile, int pidx, int pcnt) {
;     const int tid = opaque_tid(wv); const int ntk = Ksrc / 128; const int total = ntn * ntk; const int G = pcnt;
;     const int kk0 = tid >> 4, n4 = (tid & 15) * 4;
;     f32x4 v[4]; float ks[4];
;     auto prefetch = [&](int t) {
;         const int tn = t % ntn, tk = t / ntn; const int n0 = tn * 64, k0 = tk * 128;
;         int scol = n0, nvalid = 64;
;         if (mode == 1) { if (n0 < 5632) scol = n0; else if (n0 < 13312) scol = n0 + 8; else if (n0 == 13312) { scol = 5632; nvalid = 8; } else { scol = 0; nvalid = 0; } }
; #pragma unroll
;         for (int i = 0; i < 4; ++i) { const int kk = kk0 + i * 32; v[i] = (f32x4){0.f, 0.f, 0.f, 0.f};
;             if (n4 < nvalid) v[i] = *(const f32x4*)(src + (size_t)(k0 + kk) * ldsrc + scol + n4);
;             ks[i] = kscale ? kscale[k0 + kk] : 1.0f; }
;     };
;     int t = pidx; int buf = 0;
;     if (t < total) prefetch(t);
; __device__ __forceinline__ void convert_layer(int wv, PP P, int L, int mask, LAS float* tile, int pidx, int pcnt) {
;     ...
;         convert_weight(wv, P->w_br_a + (size_t)L * 512 * D, D, 512, wbr, D, 0, D / 64, nullptr, 0, tile, pidx, pcnt);
.LBB0_771:
	v_readlane_b32 s4, v254, 30
	v_readlane_b32 s5, v254, 31
	s_and_b64 vcc, exec, s[4:5]
	s_branch .LBB0_802
	s_mov_b32 s4, s81
	v_readlane_b32 s5, v254, 7
	s_cmp_lt_i32 s4, s5
	v_readlane_b32 s8, v254, 5
	s_cselect_b64 s[6:7], -1, 0
	v_readlane_b32 s9, v254, 6
	s_or_b64 s[6:7], s[8:9], s[6:7]
	s_and_b64 vcc, exec, s[6:7]
	s_cbranch_vccnz .LBB0_802
	s_mov_b64 s[6:7], s[0:1]
	v_readlane_b32 s5, v254, 7
	s_sub_i32 s18, s4, s5
	s_load_dwordx2 s[4:5], s[6:7], 0x98
	s_cmpk_lt_i32 s18, 0x80
	s_mov_b32 s14, s95
	v_mov_b32_e32 v0, v3
	s_cselect_b64 s[8:9], -1, 0
	s_cmpk_gt_i32 s18, 0x7f
	s_cbranch_scc1 .LBB0_780
	s_load_dwordx2 s[12:13], s[6:7], 0x48
	s_waitcnt lgkmcnt(0)
	s_add_u32 s10, s4, 0x4200000
	v_mbcnt_lo_u32_b32 v0, -1, v0
	s_addc_u32 s11, s5, 0
	v_mbcnt_hi_u32_b32 v20, -1, v0
	s_add_u32 s12, s12, 0x400000
	v_lshl_or_b32 v21, s14, 6, v20
	s_sext_i32_i16 s14, s18
	s_addc_u32 s13, s13, 0
	s_bfe_u32 s14, s14, 0x5001a
	s_add_i32 s14, s18, s14
	s_sext_i32_i16 s15, s14
	v_ashrrev_i32_e32 v22, 4, v21
	s_and_b32 s14, s14, 0xffe0
	s_lshl_b32 s15, s15, 2
	v_lshlrev_b32_e32 v0, 2, v20
	s_sub_i32 s14, s18, s14
	s_and_b32 s16, s15, 0xffffff80
	v_add_u32_e32 v23, 32, v22
	v_add_u32_e32 v24, 64, v22
	v_add_u32_e32 v25, 0x60, v22
	v_and_b32_e32 v2, 60, v0
	s_sext_i32_i16 s14, s14
	v_add_u32_e32 v0, s16, v22
	v_add_u32_e32 v6, s16, v23
	v_add_u32_e32 v12, s16, v24
	v_add_u32_e32 v14, s16, v25
	s_lshl_b32 s14, s14, 6
	v_ashrrev_i32_e32 v1, 31, v0
	v_ashrrev_i32_e32 v7, 31, v6
	v_ashrrev_i32_e32 v13, 31, v12
	v_ashrrev_i32_e32 v15, 31, v14
	s_ashr_i32 s15, s14, 31
	v_lshlrev_b64 v[0:1], 13, v[0:1]
	v_lshlrev_b64 v[6:7], 13, v[6:7]
	v_lshlrev_b64 v[12:13], 13, v[12:13]
	v_lshlrev_b64 v[14:15], 13, v[14:15]
	v_lshl_add_u64 v[0:1], s[12:13], 0, v[0:1]
	s_lshl_b64 s[14:15], s[14:15], 2
	v_lshl_add_u64 v[6:7], s[12:13], 0, v[6:7]
	v_lshl_add_u64 v[12:13], s[12:13], 0, v[12:13]
	v_lshl_add_u64 v[14:15], s[12:13], 0, v[14:15]
	v_lshl_add_u64 v[4:5], v[0:1], 0, s[14:15]
	v_lshlrev_b32_e32 v0, 2, v2
	v_mov_b32_e32 v1, v3
	v_lshl_add_u64 v[6:7], v[6:7], 0, s[14:15]
	v_lshl_add_u64 v[12:13], v[12:13], 0, s[14:15]
	v_lshl_add_u64 v[14:15], v[14:15], 0, s[14:15]
	v_lshl_add_u64 v[4:5], v[4:5], 0, v[0:1]
	v_lshl_add_u64 v[8:9], v[6:7], 0, v[0:1]
	v_lshl_add_u64 v[12:13], v[12:13], 0, v[0:1]
	v_lshl_add_u64 v[16:17], v[14:15], 0, v[0:1]
	global_load_dwordx4 v[4:7], v[4:5], off
	s_nop 0
	global_load_dwordx4 v[8:11], v[8:9], off
	s_nop 0
	global_load_dwordx4 v[12:15], v[12:13], off
	s_nop 0
	global_load_dwordx4 v[16:19], v[16:17], off
	v_lshlrev_b32_e32 v20, 4, v20
	v_and_b32_e32 v28, 0x70, v20
	v_readlane_b32 s14, v254, 8
	v_ashrrev_i32_e32 v1, 3, v21
	v_mul_u32_u24_e32 v26, 0x104, v28
	v_mul_lo_u32 v27, v22, s87
	s_lshl_b32 s21, s18, 6
	s_lshl_b32 s19, s14, 6
	s_mov_b32 s20, 0
	v_lshlrev_b32_e32 v20, 2, v2
	v_lshlrev_b32_e32 v2, 1, v28
	s_mov_b32 s24, s18
	s_waitcnt vmcnt(0)
	s_branch .LBB0_776
